# P1 [u|gate] epilogue rewritten with packed f32 ops (same formula); P2 unit head rewritten (all loads up front, counted waits, rstd via b128+cndmask); P1 loop-top lgkmcnt moved above first ds_read; att
# speedup vs baseline: 1.1662x; 1.0110x over previous
; #define PG8_STAGE(bufoff, gbase, voff) do { _Pragma("unroll") for (int _i = 0; _i < 2; ++_i) \
;         __builtin_amdgcn_global_load_lds((const unsigned*)((const char*)(gbase) + (voff)[_i]), (PG8_LAS unsigned*)(lds + (bufoff) + ldsw + _i * 8192), 16, 0, 0); } while (0)
; #define PG8_LDA(dst, b, h) do { _Pragma("unroll") for (int m = 0; m < 4; ++m) _Pragma("unroll") for (int k = 0; k < 2; ++k) dst[m][k] = *(const PG8_LAS bf16x8*)(lds + PG8_SA(b, h) + aoff + m * 2048 + k * 1024); } while (0)
; #define PG8_LDB(dst, b, h) do { _Pragma("unroll") for (int n = 0; n < 2; ++n) _Pragma("unroll") for (int k = 0; k < 2; ++k) dst[n][k] = *(const PG8_LAS bf16x8*)(lds + PG8_SB(b, h) + boff + n * 2048 + k * 1024); } while (0)
; #define PG8_MMA(ai, bj, At, Bt) do { __builtin_amdgcn_s_setprio(1); _Pragma("unroll") for (int m = 0; m < 4; ++m) _Pragma("unroll") for (int n = 0; n < 2; ++n) _Pragma("unroll") for (int k = 0; k < 2; ++k) \
;         acc[ai][bj][m][n] = __builtin_amdgcn_mfma_f32_16x16x32_bf16(Bt[n][k], At[m][k], acc[ai][bj][m][n], 0, 0, 0); __builtin_amdgcn_s_setprio(0); } while (0)
; #define PG8_WAIT_V(n) asm volatile("s_waitcnt vmcnt(" #n ")" ::: "memory")
; #define PG8_WAIT_L(n) asm volatile("s_waitcnt lgkmcnt(" #n ")" ::: "memory")
; #define PG8_BAR __builtin_amdgcn_s_barrier()
; #define PG8_SCHED __builtin_amdgcn_sched_barrier(0)
; template <class Epi, class Sched, bool ALIGN_EPI = false, bool SP2 = false>
; __device__ __forceinline__ void gemm_phase(PG8_LAS unsigned char* lds, const Gemm g, const Sched& S, const Epi& E, const int wave_) {
;     ...
;             PG8_LDB(B0, 0, 0); PG8_LDB(B1, 0, 1); PG8_SCHED; PG8_LDA(At, 0, 0); PG8_STAGE(PG8_SA(1, 1), a1 + hstep, voffA);
;             PG8_WAIT_V(8); PG8_WAIT_L(0); PG8_BAR; PG8_MMA(0, 0, At, B0); PG8_MMA(0, 1, At, B1); PG8_BAR; PG8_SCHED;
;             PG8_LDA(At, 0, 1); PG8_STAGE(PG8_SB(0, 0), b2, voffB); PG8_STAGE(PG8_SB(0, 1), b2 + hstep, voffB); PG8_STAGE(PG8_SA(0, 0), a2, voffA);
;             PG8_WAIT_V(8); PG8_WAIT_L(0); PG8_BAR; PG8_MMA(1, 0, At, B0); PG8_MMA(1, 1, At, B1); PG8_BAR; PG8_SCHED;
.LBB0_129:
	s_waitcnt lgkmcnt(0)
	ds_read_b128 v[158:161], v202
	ds_read_b128 v[162:165], v202 offset:1024
	ds_read_b128 v[166:169], v202 offset:2048
	ds_read_b128 v[170:173], v202 offset:3072
	ds_read_b128 v[174:177], v205
	ds_read_b128 v[178:181], v205 offset:1024
	ds_read_b128 v[182:185], v205 offset:2048
	ds_read_b128 v[186:189], v205 offset:3072
	s_add_u32 s23, s46, 0xfff80080
	s_addc_u32 s24, s47, -1
	s_cmp_eq_u32 s22, 28
	s_cselect_b32 s51, s19, s24
	s_cselect_b32 s50, s39, s23
	s_cselect_b32 s49, s37, s97
	s_cselect_b32 s48, vcc_lo, vcc_hi
	v_lshl_add_u64 v[238:239], s[46:47], 0, v[148:149]
	s_add_i32 m0, s53, 0xc000
	ds_read_b128 v[206:209], v203
	ds_read_b128 v[210:213], v203 offset:1024
	ds_read_b128 v[214:217], v203 offset:2048
	ds_read_b128 v[218:221], v203 offset:3072
	ds_read_b128 v[222:225], v203 offset:4096
	ds_read_b128 v[226:229], v203 offset:5120
	ds_read_b128 v[230:233], v203 offset:6144
	ds_read_b128 v[234:237], v203 offset:7168
	global_load_lds_dwordx4 v[238:239], off
	v_lshl_add_u64 v[238:239], s[46:47], 0, v[150:151]
	s_add_i32 m0, s53, 0xe000
	s_nop 0
	global_load_lds_dwordx4 v[238:239], off
	s_waitcnt vmcnt(8)
	s_waitcnt lgkmcnt(0)
	s_barrier
	s_setprio 1
	s_waitcnt lgkmcnt(0)
	v_mfma_f32_16x16x32_bf16 v[124:127], v[158:161], v[206:209], v[124:127]
	v_mfma_f32_16x16x32_bf16 v[116:119], v[166:169], v[206:209], v[116:119]
	v_mfma_f32_16x16x32_bf16 v[108:111], v[158:161], v[214:217], v[108:111]
	v_mfma_f32_16x16x32_bf16 v[100:103], v[166:169], v[214:217], v[100:103]
	v_mfma_f32_16x16x32_bf16 v[92:95], v[158:161], v[222:225], v[92:95]
	v_mfma_f32_16x16x32_bf16 v[84:87], v[166:169], v[222:225], v[84:87]
	v_mfma_f32_16x16x32_bf16 v[76:79], v[158:161], v[230:233], v[76:79]
	v_mfma_f32_16x16x32_bf16 v[68:71], v[166:169], v[230:233], v[68:71]
	v_mfma_f32_16x16x32_bf16 v[124:127], v[162:165], v[210:213], v[124:127]
	v_mfma_f32_16x16x32_bf16 v[116:119], v[170:173], v[210:213], v[116:119]
	v_mfma_f32_16x16x32_bf16 v[108:111], v[162:165], v[218:221], v[108:111]
	v_mfma_f32_16x16x32_bf16 v[100:103], v[170:173], v[218:221], v[100:103]
	v_mfma_f32_16x16x32_bf16 v[92:95], v[162:165], v[226:229], v[92:95]
	v_mfma_f32_16x16x32_bf16 v[84:87], v[170:173], v[226:229], v[84:87]
	v_mfma_f32_16x16x32_bf16 v[76:79], v[162:165], v[234:237], v[76:79]
	v_mfma_f32_16x16x32_bf16 v[68:71], v[170:173], v[234:237], v[68:71]
	s_setprio 0
	s_setprio 1
	v_mfma_f32_16x16x32_bf16 v[120:123], v[174:177], v[206:209], v[120:123]
	v_mfma_f32_16x16x32_bf16 v[112:115], v[182:185], v[206:209], v[112:115]
	v_mfma_f32_16x16x32_bf16 v[104:107], v[174:177], v[214:217], v[104:107]
	v_mfma_f32_16x16x32_bf16 v[96:99], v[182:185], v[214:217], v[96:99]
	v_mfma_f32_16x16x32_bf16 v[88:91], v[174:177], v[222:225], v[88:91]
	v_mfma_f32_16x16x32_bf16 v[80:83], v[182:185], v[222:225], v[80:83]
	v_mfma_f32_16x16x32_bf16 v[72:75], v[174:177], v[230:233], v[72:75]
	v_mfma_f32_16x16x32_bf16 v[64:67], v[182:185], v[230:233], v[64:67]
	v_mfma_f32_16x16x32_bf16 v[120:123], v[178:181], v[210:213], v[120:123]
	v_mfma_f32_16x16x32_bf16 v[112:115], v[186:189], v[210:213], v[112:115]
	v_mfma_f32_16x16x32_bf16 v[104:107], v[178:181], v[218:221], v[104:107]
	v_mfma_f32_16x16x32_bf16 v[96:99], v[186:189], v[218:221], v[96:99]
	v_mfma_f32_16x16x32_bf16 v[88:91], v[178:181], v[226:229], v[88:91]
	v_mfma_f32_16x16x32_bf16 v[80:83], v[186:189], v[226:229], v[80:83]
	v_mfma_f32_16x16x32_bf16 v[72:75], v[178:181], v[234:237], v[72:75]
	v_mfma_f32_16x16x32_bf16 v[64:67], v[186:189], v[234:237], v[64:67]
	s_setprio 0
	s_barrier
	s_add_i32 s23, s67, s52
	v_lshl_add_u64 v[238:239], s[48:49], 0, v[130:131]
	s_mov_b32 m0, s23
	ds_read_b128 v[206:209], v203 offset:16384
	ds_read_b128 v[210:213], v203 offset:17408
	ds_read_b128 v[214:217], v203 offset:18432
	ds_read_b128 v[218:221], v203 offset:19456
	ds_read_b128 v[222:225], v203 offset:20480
	ds_read_b128 v[226:229], v203 offset:21504
	ds_read_b128 v[230:233], v203 offset:22528
	ds_read_b128 v[234:237], v203 offset:23552
	global_load_lds_dwordx4 v[238:239], off
	s_add_i32 m0, s23, 0x2000
	s_add_u32 s24, s48, 0x80000
	v_lshl_add_u64 v[240:241], s[48:49], 0, v[134:135]
	s_addc_u32 s25, s49, 0
	s_add_i32 s23, s71, s52
	global_load_lds_dwordx4 v[240:241], off
	v_lshl_add_u64 v[242:243], s[24:25], 0, v[130:131]
	s_mov_b32 m0, s23
	v_lshl_add_u64 v[244:245], s[50:51], 0, v[132:133]
	global_load_lds_dwordx4 v[242:243], off
	v_lshl_add_u64 v[242:243], s[24:25], 0, v[134:135]
	s_add_i32 m0, s23, 0x2000
	s_nop 0
	global_load_lds_dwordx4 v[242:243], off
	v_lshl_add_u64 v[242:243], s[50:51], 0, v[128:129]
	s_mov_b32 m0, s53
	s_nop 0
	global_load_lds_dwordx4 v[242:243], off
	s_mov_b32 m0, s54
	s_nop 0
	global_load_lds_dwordx4 v[244:245], off
	s_waitcnt vmcnt(8)
	s_waitcnt lgkmcnt(0)
	s_barrier
; #define PG8_STAGE(bufoff, gbase, voff) do { _Pragma("unroll") for (int _i = 0; _i < 2; ++_i) \
;         __builtin_amdgcn_global_load_lds((const unsigned*)((const char*)(gbase) + (voff)[_i]), (PG8_LAS unsigned*)(lds + (bufoff) + ldsw + _i * 8192), 16, 0, 0); } while (0)
; #define PG8_LDA(dst, b, h) do { _Pragma("unroll") for (int m = 0; m < 4; ++m) _Pragma("unroll") for (int k = 0; k < 2; ++k) dst[m][k] = *(const PG8_LAS bf16x8*)(lds + PG8_SA(b, h) + aoff + m * 2048 + k * 1024); } while (0)
; #define PG8_LDB(dst, b, h) do { _Pragma("unroll") for (int n = 0; n < 2; ++n) _Pragma("unroll") for (int k = 0; k < 2; ++k) dst[n][k] = *(const PG8_LAS bf16x8*)(lds + PG8_SB(b, h) + boff + n * 2048 + k * 1024); } while (0)
; #define PG8_MMA(ai, bj, At, Bt) do { __builtin_amdgcn_s_setprio(1); _Pragma("unroll") for (int m = 0; m < 4; ++m) _Pragma("unroll") for (int n = 0; n < 2; ++n) _Pragma("unroll") for (int k = 0; k < 2; ++k) \
;         acc[ai][bj][m][n] = __builtin_amdgcn_mfma_f32_16x16x32_bf16(Bt[n][k], At[m][k], acc[ai][bj][m][n], 0, 0, 0); __builtin_amdgcn_s_setprio(0); } while (0)
; #define PG8_WAIT_V(n) asm volatile("s_waitcnt vmcnt(" #n ")" ::: "memory")
; #define PG8_WAIT_L(n) asm volatile("s_waitcnt lgkmcnt(" #n ")" ::: "memory")
; #define PG8_BAR __builtin_amdgcn_s_barrier()
; #define PG8_SCHED __builtin_amdgcn_sched_barrier(0)
; template <class Epi, class Sched, bool ALIGN_EPI = false, bool SP2 = false>
; __device__ __forceinline__ void gemm_phase(PG8_LAS unsigned char* lds, const Gemm g, const Sched& S, const Epi& E, const int wave_) {
;     ...
;             PG8_WAIT_V(8); PG8_WAIT_L(0); PG8_BAR; PG8_MMA(1, 0, At, B0); PG8_MMA(1, 1, At, B1); PG8_BAR; PG8_SCHED;
;             PG8_LDB(B0, 1, 0); PG8_LDB(B1, 1, 1); PG8_SCHED; PG8_LDA(At, 1, 0); PG8_STAGE(PG8_SA(0, 1), a2 + hstep, voffA);
;             PG8_WAIT_V(8); PG8_WAIT_L(0); PG8_BAR; PG8_MMA(0, 0, At, B0); PG8_MMA(0, 1, At, B1); PG8_BAR; PG8_SCHED;
	s_setprio 1
	s_waitcnt lgkmcnt(0)
	v_mfma_f32_16x16x32_bf16 v[60:63], v[158:161], v[206:209], v[60:63]
	v_mfma_f32_16x16x32_bf16 v[52:55], v[166:169], v[206:209], v[52:55]
	v_mfma_f32_16x16x32_bf16 v[44:47], v[158:161], v[214:217], v[44:47]
	v_mfma_f32_16x16x32_bf16 v[36:39], v[166:169], v[214:217], v[36:39]
	v_mfma_f32_16x16x32_bf16 v[28:31], v[158:161], v[222:225], v[28:31]
	v_mfma_f32_16x16x32_bf16 v[20:23], v[166:169], v[222:225], v[20:23]
	v_mfma_f32_16x16x32_bf16 v[12:15], v[158:161], v[230:233], v[12:15]
	v_mfma_f32_16x16x32_bf16 v[4:7], v[166:169], v[230:233], v[4:7]
	v_mfma_f32_16x16x32_bf16 v[60:63], v[162:165], v[210:213], v[60:63]
	v_mfma_f32_16x16x32_bf16 v[52:55], v[170:173], v[210:213], v[52:55]
	v_mfma_f32_16x16x32_bf16 v[44:47], v[162:165], v[218:221], v[44:47]
	v_mfma_f32_16x16x32_bf16 v[36:39], v[170:173], v[218:221], v[36:39]
	v_mfma_f32_16x16x32_bf16 v[28:31], v[162:165], v[226:229], v[28:31]
	v_mfma_f32_16x16x32_bf16 v[20:23], v[170:173], v[226:229], v[20:23]
	v_mfma_f32_16x16x32_bf16 v[12:15], v[162:165], v[234:237], v[12:15]
	v_mfma_f32_16x16x32_bf16 v[4:7], v[170:173], v[234:237], v[4:7]
	s_setprio 0
	s_setprio 1
	v_mfma_f32_16x16x32_bf16 v[56:59], v[174:177], v[206:209], v[56:59]
	v_mfma_f32_16x16x32_bf16 v[48:51], v[182:185], v[206:209], v[48:51]
	v_mfma_f32_16x16x32_bf16 v[40:43], v[174:177], v[214:217], v[40:43]
	v_mfma_f32_16x16x32_bf16 v[32:35], v[182:185], v[214:217], v[32:35]
	v_mfma_f32_16x16x32_bf16 v[24:27], v[174:177], v[222:225], v[24:27]
	v_mfma_f32_16x16x32_bf16 v[16:19], v[182:185], v[222:225], v[16:19]
	v_mfma_f32_16x16x32_bf16 v[8:11], v[174:177], v[230:233], v[8:11]
	v_mfma_f32_16x16x32_bf16 v[0:3], v[182:185], v[230:233], v[0:3]
	v_mfma_f32_16x16x32_bf16 v[56:59], v[178:181], v[210:213], v[56:59]
	v_mfma_f32_16x16x32_bf16 v[48:51], v[186:189], v[210:213], v[48:51]
	v_mfma_f32_16x16x32_bf16 v[40:43], v[178:181], v[218:221], v[40:43]
	v_mfma_f32_16x16x32_bf16 v[32:35], v[186:189], v[218:221], v[32:35]
	v_mfma_f32_16x16x32_bf16 v[24:27], v[178:181], v[226:229], v[24:27]
	v_mfma_f32_16x16x32_bf16 v[16:19], v[186:189], v[226:229], v[16:19]
	v_mfma_f32_16x16x32_bf16 v[8:11], v[178:181], v[234:237], v[8:11]
	v_mfma_f32_16x16x32_bf16 v[0:3], v[186:189], v[234:237], v[0:3]
	s_setprio 0
	s_barrier
	s_add_i32 s23, 0, 0x18000
	s_add_i32 s86, 0, 0x1c000
	v_add_u32_e32 v170, s23, v191
	v_add_u32_e32 v186, s86, v191
	ds_read_b128 v[158:161], v170
	ds_read_b128 v[162:165], v170 offset:1024
	ds_read_b128 v[166:169], v170 offset:2048
	ds_read_b128 v[170:173], v170 offset:3072
	ds_read_b128 v[174:177], v186
	ds_read_b128 v[178:181], v186 offset:1024
	ds_read_b128 v[182:185], v186 offset:2048
	ds_read_b128 v[186:189], v186 offset:3072
	s_add_u32 s24, s50, 0x80000
	s_addc_u32 s25, s51, 0
	s_mov_b32 m0, s55
	v_lshl_add_u64 v[246:247], s[24:25], 0, v[128:129]
	ds_read_b128 v[206:209], v203 offset:32768
	ds_read_b128 v[210:213], v203 offset:33792
	ds_read_b128 v[214:217], v203 offset:34816
	ds_read_b128 v[218:221], v203 offset:35840
	ds_read_b128 v[222:225], v203 offset:36864
	ds_read_b128 v[226:229], v203 offset:37888
	ds_read_b128 v[230:233], v203 offset:38912
	ds_read_b128 v[234:237], v203 offset:39936
	global_load_lds_dwordx4 v[246:247], off
	v_lshl_add_u64 v[246:247], s[24:25], 0, v[132:133]
	s_mov_b32 m0, s56
	s_nop 0
	global_load_lds_dwordx4 v[246:247], off
	s_waitcnt vmcnt(8)
	s_waitcnt lgkmcnt(0)
	s_barrier
	s_setprio 1
	s_waitcnt lgkmcnt(0)
	v_mfma_f32_16x16x32_bf16 v[124:127], v[158:161], v[206:209], v[124:127]
	v_mfma_f32_16x16x32_bf16 v[116:119], v[166:169], v[206:209], v[116:119]
	v_mfma_f32_16x16x32_bf16 v[108:111], v[158:161], v[214:217], v[108:111]
	v_mfma_f32_16x16x32_bf16 v[100:103], v[166:169], v[214:217], v[100:103]
	v_mfma_f32_16x16x32_bf16 v[92:95], v[158:161], v[222:225], v[92:95]
	v_mfma_f32_16x16x32_bf16 v[84:87], v[166:169], v[222:225], v[84:87]
	v_mfma_f32_16x16x32_bf16 v[76:79], v[158:161], v[230:233], v[76:79]
	v_mfma_f32_16x16x32_bf16 v[68:71], v[166:169], v[230:233], v[68:71]
	v_mfma_f32_16x16x32_bf16 v[124:127], v[162:165], v[210:213], v[124:127]
	v_mfma_f32_16x16x32_bf16 v[116:119], v[170:173], v[210:213], v[116:119]
	v_mfma_f32_16x16x32_bf16 v[108:111], v[162:165], v[218:221], v[108:111]
	v_mfma_f32_16x16x32_bf16 v[100:103], v[170:173], v[218:221], v[100:103]
	v_mfma_f32_16x16x32_bf16 v[92:95], v[162:165], v[226:229], v[92:95]
	v_mfma_f32_16x16x32_bf16 v[84:87], v[170:173], v[226:229], v[84:87]
	v_mfma_f32_16x16x32_bf16 v[76:79], v[162:165], v[234:237], v[76:79]
	v_mfma_f32_16x16x32_bf16 v[68:71], v[170:173], v[234:237], v[68:71]
	s_setprio 0
	s_setprio 1
	v_mfma_f32_16x16x32_bf16 v[120:123], v[174:177], v[206:209], v[120:123]
	v_mfma_f32_16x16x32_bf16 v[112:115], v[182:185], v[206:209], v[112:115]
	v_mfma_f32_16x16x32_bf16 v[104:107], v[174:177], v[214:217], v[104:107]
	v_mfma_f32_16x16x32_bf16 v[96:99], v[182:185], v[214:217], v[96:99]
	v_mfma_f32_16x16x32_bf16 v[88:91], v[174:177], v[222:225], v[88:91]
	v_mfma_f32_16x16x32_bf16 v[80:83], v[182:185], v[222:225], v[80:83]
	v_mfma_f32_16x16x32_bf16 v[72:75], v[174:177], v[230:233], v[72:75]
	v_mfma_f32_16x16x32_bf16 v[64:67], v[182:185], v[230:233], v[64:67]
	v_mfma_f32_16x16x32_bf16 v[120:123], v[178:181], v[210:213], v[120:123]
	v_mfma_f32_16x16x32_bf16 v[112:115], v[186:189], v[210:213], v[112:115]
	v_mfma_f32_16x16x32_bf16 v[104:107], v[178:181], v[218:221], v[104:107]
	v_mfma_f32_16x16x32_bf16 v[96:99], v[186:189], v[218:221], v[96:99]
	v_mfma_f32_16x16x32_bf16 v[88:91], v[178:181], v[226:229], v[88:91]
	v_mfma_f32_16x16x32_bf16 v[80:83], v[186:189], v[226:229], v[80:83]
	v_mfma_f32_16x16x32_bf16 v[72:75], v[178:181], v[234:237], v[72:75]
	v_mfma_f32_16x16x32_bf16 v[64:67], v[186:189], v[234:237], v[64:67]
	s_setprio 0
	s_barrier
; #define PG8_STAGE(bufoff, gbase, voff) do { _Pragma("unroll") for (int _i = 0; _i < 2; ++_i) \
;         __builtin_amdgcn_global_load_lds((const unsigned*)((const char*)(gbase) + (voff)[_i]), (PG8_LAS unsigned*)(lds + (bufoff) + ldsw + _i * 8192), 16, 0, 0); } while (0)
; #define PG8_LDA(dst, b, h) do { _Pragma("unroll") for (int m = 0; m < 4; ++m) _Pragma("unroll") for (int k = 0; k < 2; ++k) dst[m][k] = *(const PG8_LAS bf16x8*)(lds + PG8_SA(b, h) + aoff + m * 2048 + k * 1024); } while (0)
; #define PG8_MMA(ai, bj, At, Bt) do { __builtin_amdgcn_s_setprio(1); _Pragma("unroll") for (int m = 0; m < 4; ++m) _Pragma("unroll") for (int n = 0; n < 2; ++n) _Pragma("unroll") for (int k = 0; k < 2; ++k) \
;         acc[ai][bj][m][n] = __builtin_amdgcn_mfma_f32_16x16x32_bf16(Bt[n][k], At[m][k], acc[ai][bj][m][n], 0, 0, 0); __builtin_amdgcn_s_setprio(0); } while (0)
; #define PG8_WAIT_V(n) asm volatile("s_waitcnt vmcnt(" #n ")" ::: "memory")
; #define PG8_WAIT_L(n) asm volatile("s_waitcnt lgkmcnt(" #n ")" ::: "memory")
; #define PG8_BAR __builtin_amdgcn_s_barrier()
; #define PG8_SCHED __builtin_amdgcn_sched_barrier(0)
; template <class Epi, class Sched, bool ALIGN_EPI = false, bool SP2 = false>
; __device__ __forceinline__ void gemm_phase(PG8_LAS unsigned char* lds, const Gemm g, const Sched& S, const Epi& E, const int wave_) {
;     ...
;             PG8_LDA(At, 1, 1); PG8_STAGE(PG8_SB(1, 0), b3, voffB); PG8_STAGE(PG8_SB(1, 1), b3 + hstep, voffB); PG8_STAGE(PG8_SA(1, 0), a3, voffA);
;             PG8_WAIT_V(8); PG8_WAIT_L(0); PG8_BAR; PG8_MMA(1, 0, At, B0); PG8_MMA(1, 1, At, B1); PG8_BAR; PG8_SCHED;
;     ...
;         if constexpr (ALIGN_EPI) { if (wr == 0) PG8_BAR; }
	s_add_i32 s23, s23, s52
	v_lshl_add_u64 v[238:239], v[238:239], 0, s[34:35]
	s_mov_b32 m0, s23
	ds_read_b128 v[206:209], v203 offset:49152
	ds_read_b128 v[210:213], v203 offset:50176
	ds_read_b128 v[214:217], v203 offset:51200
	ds_read_b128 v[218:221], v203 offset:52224
	ds_read_b128 v[222:225], v203 offset:53248
	ds_read_b128 v[226:229], v203 offset:54272
	ds_read_b128 v[230:233], v203 offset:55296
	ds_read_b128 v[234:237], v203 offset:56320
	global_load_lds_dwordx4 v[238:239], off
	s_add_i32 m0, s23, 0x2000
	s_add_u32 s24, s48, 0x80080
	v_lshl_add_u64 v[238:239], v[240:241], 0, s[34:35]
	s_addc_u32 s25, s49, 0
	s_add_i32 s23, s86, s52
	global_load_lds_dwordx4 v[238:239], off
	v_lshl_add_u64 v[238:239], s[24:25], 0, v[130:131]
	s_mov_b32 m0, s23
	s_nop 0
	global_load_lds_dwordx4 v[238:239], off
	v_lshl_add_u64 v[238:239], s[24:25], 0, v[134:135]
	s_add_i32 m0, s23, 0x2000
	s_nop 0
	global_load_lds_dwordx4 v[238:239], off
	v_lshl_add_u64 v[238:239], v[242:243], 0, s[34:35]
	s_mov_b32 m0, s64
	s_nop 0
	global_load_lds_dwordx4 v[238:239], off
	v_lshl_add_u64 v[238:239], v[244:245], 0, s[34:35]
	s_mov_b32 m0, s65
	s_nop 0
	global_load_lds_dwordx4 v[238:239], off
	s_waitcnt vmcnt(8)
	s_waitcnt lgkmcnt(0)
	s_barrier
	s_setprio 1
	s_waitcnt lgkmcnt(0)
	v_mfma_f32_16x16x32_bf16 v[60:63], v[158:161], v[206:209], v[60:63]
	v_mfma_f32_16x16x32_bf16 v[52:55], v[166:169], v[206:209], v[52:55]
	v_mfma_f32_16x16x32_bf16 v[44:47], v[158:161], v[214:217], v[44:47]
	v_mfma_f32_16x16x32_bf16 v[36:39], v[166:169], v[214:217], v[36:39]
	v_mfma_f32_16x16x32_bf16 v[28:31], v[158:161], v[222:225], v[28:31]
	v_mfma_f32_16x16x32_bf16 v[20:23], v[166:169], v[222:225], v[20:23]
	v_mfma_f32_16x16x32_bf16 v[12:15], v[158:161], v[230:233], v[12:15]
	v_mfma_f32_16x16x32_bf16 v[4:7], v[166:169], v[230:233], v[4:7]
	v_mfma_f32_16x16x32_bf16 v[60:63], v[162:165], v[210:213], v[60:63]
	v_mfma_f32_16x16x32_bf16 v[52:55], v[170:173], v[210:213], v[52:55]
	v_mfma_f32_16x16x32_bf16 v[44:47], v[162:165], v[218:221], v[44:47]
	v_mfma_f32_16x16x32_bf16 v[36:39], v[170:173], v[218:221], v[36:39]
	v_mfma_f32_16x16x32_bf16 v[28:31], v[162:165], v[226:229], v[28:31]
	v_mfma_f32_16x16x32_bf16 v[20:23], v[170:173], v[226:229], v[20:23]
	v_mfma_f32_16x16x32_bf16 v[12:15], v[162:165], v[234:237], v[12:15]
	v_mfma_f32_16x16x32_bf16 v[4:7], v[170:173], v[234:237], v[4:7]
	s_setprio 0
	s_setprio 1
	v_mfma_f32_16x16x32_bf16 v[56:59], v[174:177], v[206:209], v[56:59]
	v_mfma_f32_16x16x32_bf16 v[48:51], v[182:185], v[206:209], v[48:51]
	v_mfma_f32_16x16x32_bf16 v[40:43], v[174:177], v[214:217], v[40:43]
	v_mfma_f32_16x16x32_bf16 v[32:35], v[182:185], v[214:217], v[32:35]
	v_mfma_f32_16x16x32_bf16 v[24:27], v[174:177], v[222:225], v[24:27]
	v_mfma_f32_16x16x32_bf16 v[16:19], v[182:185], v[222:225], v[16:19]
	v_mfma_f32_16x16x32_bf16 v[8:11], v[174:177], v[230:233], v[8:11]
	v_mfma_f32_16x16x32_bf16 v[0:3], v[182:185], v[230:233], v[0:3]
	v_mfma_f32_16x16x32_bf16 v[56:59], v[178:181], v[210:213], v[56:59]
	v_mfma_f32_16x16x32_bf16 v[48:51], v[186:189], v[210:213], v[48:51]
	v_mfma_f32_16x16x32_bf16 v[40:43], v[178:181], v[218:221], v[40:43]
	v_mfma_f32_16x16x32_bf16 v[32:35], v[186:189], v[218:221], v[32:35]
	v_mfma_f32_16x16x32_bf16 v[24:27], v[178:181], v[226:229], v[24:27]
	v_mfma_f32_16x16x32_bf16 v[16:19], v[186:189], v[226:229], v[16:19]
	v_mfma_f32_16x16x32_bf16 v[8:11], v[178:181], v[234:237], v[8:11]
	v_mfma_f32_16x16x32_bf16 v[0:3], v[186:189], v[234:237], v[0:3]
	s_setprio 0
	s_barrier
	s_add_i32 s22, s22, 2
	s_add_u32 s46, s46, 0x100
	s_addc_u32 s47, s47, 0
	s_add_u32 vcc_hi, vcc_hi, 0x100
	s_addc_u32 s97, s97, 0
	s_cmp_gt_u32 s22, 29
	s_cbranch_scc0 .LBB0_129
	s_and_b64 vcc, exec, s[74:75]
	s_cbranch_vccz .LBB0_132
	s_barrier

; __device__ __forceinline__ unsigned cvt_pk_bf16(float lo, float hi) { unsigned r; asm volatile("v_cvt_pk_bf16_f32 %0, %1, %2" : "=v"(r) : "v"(lo), "v"(hi)); return r; }
; __device__ __forceinline__ float gelu_silu(float u, float z) {
;     const float e1 = __builtin_amdgcn_exp2f(u * __builtin_fmaf(u * u, GELU_C2, GELU_C1));
;     const float e2 = __builtin_amdgcn_exp2f(z * -LOG2E);
;     return (u * z) * __builtin_amdgcn_rcpf((1.0f + e1) * (1.0f + e2));
; }
;     __device__ __forceinline__ void operator()(const f32x4 (&acc)[2][2][4][2], const Unit& u, int wr, int wc, int fr, int fq) const {
;         const int row0 = u.pm * BM + wr * 64 + fr;
;         const int tq = u.pn / 3, tr = u.pn - 3 * tq;
;         if (tr < 2) {
;             const int col0 = (2 * tq + tr) * HALF + wc * 32 + 8 * fq;
; #pragma unroll
;             for (int ai = 0; ai < 2; ++ai)
; #pragma unroll
;                 for (int m = 0; m < 4; ++m) {
;                     const int row = row0 + ai * HALF + m * 16;
;                     f32x4 v0 = acc[ai][0][m][0], v1 = acc[ai][0][m][1]; const f32x4 z0 = acc[ai][1][m][0], z1 = acc[ai][1][m][1];
; #pragma unroll
;                     for (int e = 0; e < 4; ++e) { v0[e] = gelu_silu(v0[e], z0[e]); v1[e] = gelu_silu(v1[e], z1[e]); }
;                     u32x4 w; w.x = cvt_pk_bf16(v0[0], v0[1]); w.y = cvt_pk_bf16(v0[2], v0[3]); w.z = cvt_pk_bf16(v1[0], v1[1]); w.w = cvt_pk_bf16(v1[2], v1[3]);
;                     *(u32x4*)(UZ + (size_t)row * GW + col0) = w;
;                 }
.LBB0_152:
	s_waitcnt lgkmcnt(0)
	s_lshl_b32 s18, s37, 7
	s_add_i32 s18, s18, s39
	v_or_b32_e32 v160, s18, v192
	v_ashrrev_i32_e32 v161, 31, v160
	s_mov_b32 s100, 0xbdd2d3e7
	s_mov_b32 s101, 0xbfb8aa3b
	s_mov_b32 s99, 0
	v_lshlrev_b64 v[232:233], 13, v[158:159]
	v_lshl_add_u64 v[232:233], s[20:21], 0, v[232:233]
	v_lshlrev_b64 v[162:163], 1, v[160:161]
	v_lshl_add_u64 v[232:233], v[232:233], 0, v[162:163]
	v_pk_mul_f32 v[206:207], v[124:125], v[124:125]
	v_pk_mul_f32 v[208:209], v[126:127], v[126:127]
	v_pk_mul_f32 v[210:211], v[116:117], v[116:117]
	v_pk_mul_f32 v[212:213], v[118:119], v[118:119]
	v_pk_fma_f32 v[206:207], v[206:207], s[100:101], v[204:205] op_sel_hi:[1,0,0]
	v_pk_fma_f32 v[208:209], v[208:209], s[100:101], v[204:205] op_sel_hi:[1,0,0]
	v_pk_fma_f32 v[210:211], v[210:211], s[100:101], v[204:205] op_sel_hi:[1,0,0]
	v_pk_fma_f32 v[212:213], v[212:213], s[100:101], v[204:205] op_sel_hi:[1,0,0]
	v_pk_mul_f32 v[206:207], v[124:125], v[206:207]
	v_pk_mul_f32 v[208:209], v[126:127], v[208:209]
	v_pk_mul_f32 v[210:211], v[116:117], v[210:211]
	v_pk_mul_f32 v[212:213], v[118:119], v[212:213]
	v_pk_mul_f32 v[214:215], v[120:121], s[100:101] op_sel:[0,1] op_sel_hi:[1,1]
	v_pk_mul_f32 v[216:217], v[122:123], s[100:101] op_sel:[0,1] op_sel_hi:[1,1]
	v_pk_mul_f32 v[218:219], v[112:113], s[100:101] op_sel:[0,1] op_sel_hi:[1,1]
	v_pk_mul_f32 v[220:221], v[114:115], s[100:101] op_sel:[0,1] op_sel_hi:[1,1]
	v_pk_mul_f32 v[124:125], v[124:125], v[120:121]
	v_pk_mul_f32 v[126:127], v[126:127], v[122:123]
	v_pk_mul_f32 v[116:117], v[116:117], v[112:113]
	v_pk_mul_f32 v[118:119], v[118:119], v[114:115]
	v_exp_f32_e32 v206, v206
	v_exp_f32_e32 v207, v207
	v_exp_f32_e32 v208, v208
	v_exp_f32_e32 v209, v209
	v_exp_f32_e32 v210, v210
	v_exp_f32_e32 v211, v211
	v_exp_f32_e32 v212, v212
	v_exp_f32_e32 v213, v213
	v_exp_f32_e32 v214, v214
	v_exp_f32_e32 v215, v215
	v_exp_f32_e32 v216, v216
	v_exp_f32_e32 v217, v217
	v_exp_f32_e32 v218, v218
	v_exp_f32_e32 v219, v219
	v_exp_f32_e32 v220, v220
	v_exp_f32_e32 v221, v221
	v_pk_add_f32 v[206:207], v[206:207], 1.0 op_sel_hi:[1,0]
	v_pk_add_f32 v[208:209], v[208:209], 1.0 op_sel_hi:[1,0]
	v_pk_add_f32 v[210:211], v[210:211], 1.0 op_sel_hi:[1,0]
	v_pk_add_f32 v[212:213], v[212:213], 1.0 op_sel_hi:[1,0]
	v_pk_add_f32 v[214:215], v[214:215], 1.0 op_sel_hi:[1,0]
	v_pk_add_f32 v[216:217], v[216:217], 1.0 op_sel_hi:[1,0]
	v_pk_add_f32 v[218:219], v[218:219], 1.0 op_sel_hi:[1,0]
	v_pk_add_f32 v[220:221], v[220:221], 1.0 op_sel_hi:[1,0]
	v_pk_mul_f32 v[206:207], v[206:207], v[214:215]
	v_pk_mul_f32 v[208:209], v[208:209], v[216:217]
	v_pk_mul_f32 v[210:211], v[210:211], v[218:219]
	v_pk_mul_f32 v[212:213], v[212:213], v[220:221]
	v_rcp_f32_e32 v206, v206
	v_rcp_f32_e32 v207, v207
	v_rcp_f32_e32 v208, v208
	v_rcp_f32_e32 v209, v209
	v_rcp_f32_e32 v210, v210
	v_rcp_f32_e32 v211, v211
	v_rcp_f32_e32 v212, v212
	v_rcp_f32_e32 v213, v213
	v_mov_b32_e32 v236, v232
	v_mov_b32_e32 v237, v233
	v_pk_mul_f32 v[124:125], v[124:125], v[206:207]
	v_pk_mul_f32 v[126:127], v[126:127], v[208:209]
	v_pk_mul_f32 v[116:117], v[116:117], v[210:211]
	v_pk_mul_f32 v[118:119], v[118:119], v[212:213]
	v_cvt_pk_bf16_f32 v224, v124, v125
	v_cvt_pk_bf16_f32 v225, v126, v127
	v_cvt_pk_bf16_f32 v226, v116, v117
	v_cvt_pk_bf16_f32 v227, v118, v119
	global_store_dwordx4 v[236:237], v[224:227], off
	v_pk_mul_f32 v[206:207], v[108:109], v[108:109]
	v_pk_mul_f32 v[208:209], v[110:111], v[110:111]
	v_pk_mul_f32 v[210:211], v[100:101], v[100:101]
	v_pk_mul_f32 v[212:213], v[102:103], v[102:103]
	v_pk_fma_f32 v[206:207], v[206:207], s[100:101], v[204:205] op_sel_hi:[1,0,0]
	v_pk_fma_f32 v[208:209], v[208:209], s[100:101], v[204:205] op_sel_hi:[1,0,0]
	v_pk_fma_f32 v[210:211], v[210:211], s[100:101], v[204:205] op_sel_hi:[1,0,0]
	v_pk_fma_f32 v[212:213], v[212:213], s[100:101], v[204:205] op_sel_hi:[1,0,0]
	v_pk_mul_f32 v[206:207], v[108:109], v[206:207]
	v_pk_mul_f32 v[208:209], v[110:111], v[208:209]
	v_pk_mul_f32 v[210:211], v[100:101], v[210:211]
	v_pk_mul_f32 v[212:213], v[102:103], v[212:213]
	v_pk_mul_f32 v[214:215], v[104:105], s[100:101] op_sel:[0,1] op_sel_hi:[1,1]
	v_pk_mul_f32 v[216:217], v[106:107], s[100:101] op_sel:[0,1] op_sel_hi:[1,1]
	v_pk_mul_f32 v[218:219], v[96:97], s[100:101] op_sel:[0,1] op_sel_hi:[1,1]
	v_pk_mul_f32 v[220:221], v[98:99], s[100:101] op_sel:[0,1] op_sel_hi:[1,1]
	v_pk_mul_f32 v[108:109], v[108:109], v[104:105]
	v_pk_mul_f32 v[110:111], v[110:111], v[106:107]
	v_pk_mul_f32 v[100:101], v[100:101], v[96:97]
	v_pk_mul_f32 v[102:103], v[102:103], v[98:99]
	v_exp_f32_e32 v206, v206
	v_exp_f32_e32 v207, v207
	v_exp_f32_e32 v208, v208
	v_exp_f32_e32 v209, v209
	v_exp_f32_e32 v210, v210
	v_exp_f32_e32 v211, v211
	v_exp_f32_e32 v212, v212
	v_exp_f32_e32 v213, v213
	v_exp_f32_e32 v214, v214
	v_exp_f32_e32 v215, v215
	v_exp_f32_e32 v216, v216
	v_exp_f32_e32 v217, v217
	v_exp_f32_e32 v218, v218
	v_exp_f32_e32 v219, v219
	v_exp_f32_e32 v220, v220
	v_exp_f32_e32 v221, v221
	v_pk_add_f32 v[206:207], v[206:207], 1.0 op_sel_hi:[1,0]
	v_pk_add_f32 v[208:209], v[208:209], 1.0 op_sel_hi:[1,0]
	v_pk_add_f32 v[210:211], v[210:211], 1.0 op_sel_hi:[1,0]
	v_pk_add_f32 v[212:213], v[212:213], 1.0 op_sel_hi:[1,0]
	v_pk_add_f32 v[214:215], v[214:215], 1.0 op_sel_hi:[1,0]
	v_pk_add_f32 v[216:217], v[216:217], 1.0 op_sel_hi:[1,0]
	v_pk_add_f32 v[218:219], v[218:219], 1.0 op_sel_hi:[1,0]
	v_pk_add_f32 v[220:221], v[220:221], 1.0 op_sel_hi:[1,0]
	v_pk_mul_f32 v[206:207], v[206:207], v[214:215]
	v_pk_mul_f32 v[208:209], v[208:209], v[216:217]
	v_pk_mul_f32 v[210:211], v[210:211], v[218:219]
	v_pk_mul_f32 v[212:213], v[212:213], v[220:221]
; __device__ __forceinline__ unsigned cvt_pk_bf16(float lo, float hi) { unsigned r; asm volatile("v_cvt_pk_bf16_f32 %0, %1, %2" : "=v"(r) : "v"(lo), "v"(hi)); return r; }
; __device__ __forceinline__ float gelu_silu(float u, float z) {
;     const float e1 = __builtin_amdgcn_exp2f(u * __builtin_fmaf(u * u, GELU_C2, GELU_C1));
;     const float e2 = __builtin_amdgcn_exp2f(z * -LOG2E);
;     return (u * z) * __builtin_amdgcn_rcpf((1.0f + e1) * (1.0f + e2));
; }
;     __device__ __forceinline__ void operator()(const f32x4 (&acc)[2][2][4][2], const Unit& u, int wr, int wc, int fr, int fq) const {
;     ...
; #pragma unroll
;             for (int ai = 0; ai < 2; ++ai)
; #pragma unroll
;                 for (int m = 0; m < 4; ++m) {
;                     const int row = row0 + ai * HALF + m * 16;
;                     f32x4 v0 = acc[ai][0][m][0], v1 = acc[ai][0][m][1]; const f32x4 z0 = acc[ai][1][m][0], z1 = acc[ai][1][m][1];
; #pragma unroll
;                     for (int e = 0; e < 4; ++e) { v0[e] = gelu_silu(v0[e], z0[e]); v1[e] = gelu_silu(v1[e], z1[e]); }
;                     u32x4 w; w.x = cvt_pk_bf16(v0[0], v0[1]); w.y = cvt_pk_bf16(v0[2], v0[3]); w.z = cvt_pk_bf16(v1[0], v1[1]); w.w = cvt_pk_bf16(v1[2], v1[3]);
;                     *(u32x4*)(UZ + (size_t)row * GW + col0) = w;
;                 }
	v_rcp_f32_e32 v206, v206
	v_rcp_f32_e32 v207, v207
	v_rcp_f32_e32 v208, v208
	v_rcp_f32_e32 v209, v209
	v_rcp_f32_e32 v210, v210
	v_rcp_f32_e32 v211, v211
	v_rcp_f32_e32 v212, v212
	v_rcp_f32_e32 v213, v213
	s_mov_b32 s98, 0x20000
	v_lshl_add_u64 v[234:235], v[232:233], 0, s[98:99]
	v_pk_mul_f32 v[108:109], v[108:109], v[206:207]
	v_pk_mul_f32 v[110:111], v[110:111], v[208:209]
	v_pk_mul_f32 v[100:101], v[100:101], v[210:211]
	v_pk_mul_f32 v[102:103], v[102:103], v[212:213]
	v_cvt_pk_bf16_f32 v228, v108, v109
	v_cvt_pk_bf16_f32 v229, v110, v111
	v_cvt_pk_bf16_f32 v230, v100, v101
	v_cvt_pk_bf16_f32 v231, v102, v103
	global_store_dwordx4 v[234:235], v[228:231], off
	v_pk_mul_f32 v[206:207], v[92:93], v[92:93]
	v_pk_mul_f32 v[208:209], v[94:95], v[94:95]
	v_pk_mul_f32 v[210:211], v[84:85], v[84:85]
	v_pk_mul_f32 v[212:213], v[86:87], v[86:87]
	v_pk_fma_f32 v[206:207], v[206:207], s[100:101], v[204:205] op_sel_hi:[1,0,0]
	v_pk_fma_f32 v[208:209], v[208:209], s[100:101], v[204:205] op_sel_hi:[1,0,0]
	v_pk_fma_f32 v[210:211], v[210:211], s[100:101], v[204:205] op_sel_hi:[1,0,0]
	v_pk_fma_f32 v[212:213], v[212:213], s[100:101], v[204:205] op_sel_hi:[1,0,0]
	v_pk_mul_f32 v[206:207], v[92:93], v[206:207]
	v_pk_mul_f32 v[208:209], v[94:95], v[208:209]
	v_pk_mul_f32 v[210:211], v[84:85], v[210:211]
	v_pk_mul_f32 v[212:213], v[86:87], v[212:213]
	v_pk_mul_f32 v[214:215], v[88:89], s[100:101] op_sel:[0,1] op_sel_hi:[1,1]
	v_pk_mul_f32 v[216:217], v[90:91], s[100:101] op_sel:[0,1] op_sel_hi:[1,1]
	v_pk_mul_f32 v[218:219], v[80:81], s[100:101] op_sel:[0,1] op_sel_hi:[1,1]
	v_pk_mul_f32 v[220:221], v[82:83], s[100:101] op_sel:[0,1] op_sel_hi:[1,1]
	v_pk_mul_f32 v[92:93], v[92:93], v[88:89]
	v_pk_mul_f32 v[94:95], v[94:95], v[90:91]
	v_pk_mul_f32 v[84:85], v[84:85], v[80:81]
	v_pk_mul_f32 v[86:87], v[86:87], v[82:83]
	v_exp_f32_e32 v206, v206
	v_exp_f32_e32 v207, v207
	v_exp_f32_e32 v208, v208
	v_exp_f32_e32 v209, v209
	v_exp_f32_e32 v210, v210
	v_exp_f32_e32 v211, v211
	v_exp_f32_e32 v212, v212
	v_exp_f32_e32 v213, v213
	v_exp_f32_e32 v214, v214
	v_exp_f32_e32 v215, v215
	v_exp_f32_e32 v216, v216
	v_exp_f32_e32 v217, v217
	v_exp_f32_e32 v218, v218
	v_exp_f32_e32 v219, v219
	v_exp_f32_e32 v220, v220
	v_exp_f32_e32 v221, v221
	v_pk_add_f32 v[206:207], v[206:207], 1.0 op_sel_hi:[1,0]
	v_pk_add_f32 v[208:209], v[208:209], 1.0 op_sel_hi:[1,0]
	v_pk_add_f32 v[210:211], v[210:211], 1.0 op_sel_hi:[1,0]
	v_pk_add_f32 v[212:213], v[212:213], 1.0 op_sel_hi:[1,0]
	v_pk_add_f32 v[214:215], v[214:215], 1.0 op_sel_hi:[1,0]
	v_pk_add_f32 v[216:217], v[216:217], 1.0 op_sel_hi:[1,0]
	v_pk_add_f32 v[218:219], v[218:219], 1.0 op_sel_hi:[1,0]
	v_pk_add_f32 v[220:221], v[220:221], 1.0 op_sel_hi:[1,0]
	v_pk_mul_f32 v[206:207], v[206:207], v[214:215]
	v_pk_mul_f32 v[208:209], v[208:209], v[216:217]
	v_pk_mul_f32 v[210:211], v[210:211], v[218:219]
	v_pk_mul_f32 v[212:213], v[212:213], v[220:221]
	v_rcp_f32_e32 v206, v206
	v_rcp_f32_e32 v207, v207
	v_rcp_f32_e32 v208, v208
	v_rcp_f32_e32 v209, v209
	v_rcp_f32_e32 v210, v210
	v_rcp_f32_e32 v211, v211
	v_rcp_f32_e32 v212, v212
	v_rcp_f32_e32 v213, v213
	s_mov_b32 s98, 0x40000
	v_lshl_add_u64 v[236:237], v[232:233], 0, s[98:99]
	v_pk_mul_f32 v[92:93], v[92:93], v[206:207]
	v_pk_mul_f32 v[94:95], v[94:95], v[208:209]
	v_pk_mul_f32 v[84:85], v[84:85], v[210:211]
	v_pk_mul_f32 v[86:87], v[86:87], v[212:213]
	v_cvt_pk_bf16_f32 v224, v92, v93
	v_cvt_pk_bf16_f32 v225, v94, v95
	v_cvt_pk_bf16_f32 v226, v84, v85
	v_cvt_pk_bf16_f32 v227, v86, v87
	global_store_dwordx4 v[236:237], v[224:227], off
	v_pk_mul_f32 v[206:207], v[76:77], v[76:77]
	v_pk_mul_f32 v[208:209], v[78:79], v[78:79]
	v_pk_mul_f32 v[210:211], v[68:69], v[68:69]
	v_pk_mul_f32 v[212:213], v[70:71], v[70:71]
	v_pk_fma_f32 v[206:207], v[206:207], s[100:101], v[204:205] op_sel_hi:[1,0,0]
	v_pk_fma_f32 v[208:209], v[208:209], s[100:101], v[204:205] op_sel_hi:[1,0,0]
	v_pk_fma_f32 v[210:211], v[210:211], s[100:101], v[204:205] op_sel_hi:[1,0,0]
	v_pk_fma_f32 v[212:213], v[212:213], s[100:101], v[204:205] op_sel_hi:[1,0,0]
	v_pk_mul_f32 v[206:207], v[76:77], v[206:207]
	v_pk_mul_f32 v[208:209], v[78:79], v[208:209]
	v_pk_mul_f32 v[210:211], v[68:69], v[210:211]
	v_pk_mul_f32 v[212:213], v[70:71], v[212:213]
	v_pk_mul_f32 v[214:215], v[72:73], s[100:101] op_sel:[0,1] op_sel_hi:[1,1]
	v_pk_mul_f32 v[216:217], v[74:75], s[100:101] op_sel:[0,1] op_sel_hi:[1,1]
	v_pk_mul_f32 v[218:219], v[64:65], s[100:101] op_sel:[0,1] op_sel_hi:[1,1]
	v_pk_mul_f32 v[220:221], v[66:67], s[100:101] op_sel:[0,1] op_sel_hi:[1,1]
	v_pk_mul_f32 v[76:77], v[76:77], v[72:73]
	v_pk_mul_f32 v[78:79], v[78:79], v[74:75]
	v_pk_mul_f32 v[68:69], v[68:69], v[64:65]
	v_pk_mul_f32 v[70:71], v[70:71], v[66:67]
	v_exp_f32_e32 v206, v206
	v_exp_f32_e32 v207, v207
	v_exp_f32_e32 v208, v208
	v_exp_f32_e32 v209, v209
	v_exp_f32_e32 v210, v210
	v_exp_f32_e32 v211, v211
	v_exp_f32_e32 v212, v212
	v_exp_f32_e32 v213, v213
	v_exp_f32_e32 v214, v214
	v_exp_f32_e32 v215, v215
	v_exp_f32_e32 v216, v216
	v_exp_f32_e32 v217, v217
	v_exp_f32_e32 v218, v218
	v_exp_f32_e32 v219, v219
	v_exp_f32_e32 v220, v220
	v_exp_f32_e32 v221, v221
	v_pk_add_f32 v[206:207], v[206:207], 1.0 op_sel_hi:[1,0]
	v_pk_add_f32 v[208:209], v[208:209], 1.0 op_sel_hi:[1,0]
	v_pk_add_f32 v[210:211], v[210:211], 1.0 op_sel_hi:[1,0]
	v_pk_add_f32 v[212:213], v[212:213], 1.0 op_sel_hi:[1,0]
	v_pk_add_f32 v[214:215], v[214:215], 1.0 op_sel_hi:[1,0]
	v_pk_add_f32 v[216:217], v[216:217], 1.0 op_sel_hi:[1,0]
	v_pk_add_f32 v[218:219], v[218:219], 1.0 op_sel_hi:[1,0]
	v_pk_add_f32 v[220:221], v[220:221], 1.0 op_sel_hi:[1,0]
	v_pk_mul_f32 v[206:207], v[206:207], v[214:215]
; __device__ __forceinline__ unsigned cvt_pk_bf16(float lo, float hi) { unsigned r; asm volatile("v_cvt_pk_bf16_f32 %0, %1, %2" : "=v"(r) : "v"(lo), "v"(hi)); return r; }
; __device__ __forceinline__ float gelu_silu(float u, float z) {
;     const float e1 = __builtin_amdgcn_exp2f(u * __builtin_fmaf(u * u, GELU_C2, GELU_C1));
;     const float e2 = __builtin_amdgcn_exp2f(z * -LOG2E);
;     return (u * z) * __builtin_amdgcn_rcpf((1.0f + e1) * (1.0f + e2));
; }
;     __device__ __forceinline__ void operator()(const f32x4 (&acc)[2][2][4][2], const Unit& u, int wr, int wc, int fr, int fq) const {
;     ...
; #pragma unroll
;             for (int ai = 0; ai < 2; ++ai)
; #pragma unroll
;                 for (int m = 0; m < 4; ++m) {
;                     const int row = row0 + ai * HALF + m * 16;
;                     f32x4 v0 = acc[ai][0][m][0], v1 = acc[ai][0][m][1]; const f32x4 z0 = acc[ai][1][m][0], z1 = acc[ai][1][m][1];
; #pragma unroll
;                     for (int e = 0; e < 4; ++e) { v0[e] = gelu_silu(v0[e], z0[e]); v1[e] = gelu_silu(v1[e], z1[e]); }
;                     u32x4 w; w.x = cvt_pk_bf16(v0[0], v0[1]); w.y = cvt_pk_bf16(v0[2], v0[3]); w.z = cvt_pk_bf16(v1[0], v1[1]); w.w = cvt_pk_bf16(v1[2], v1[3]);
;                     *(u32x4*)(UZ + (size_t)row * GW + col0) = w;
;                 }
	v_pk_mul_f32 v[208:209], v[208:209], v[216:217]
	v_pk_mul_f32 v[210:211], v[210:211], v[218:219]
	v_pk_mul_f32 v[212:213], v[212:213], v[220:221]
	v_rcp_f32_e32 v206, v206
	v_rcp_f32_e32 v207, v207
	v_rcp_f32_e32 v208, v208
	v_rcp_f32_e32 v209, v209
	v_rcp_f32_e32 v210, v210
	v_rcp_f32_e32 v211, v211
	v_rcp_f32_e32 v212, v212
	v_rcp_f32_e32 v213, v213
	s_mov_b32 s98, 0x60000
	v_lshl_add_u64 v[234:235], v[232:233], 0, s[98:99]
	v_pk_mul_f32 v[76:77], v[76:77], v[206:207]
	v_pk_mul_f32 v[78:79], v[78:79], v[208:209]
	v_pk_mul_f32 v[68:69], v[68:69], v[210:211]
	v_pk_mul_f32 v[70:71], v[70:71], v[212:213]
	v_cvt_pk_bf16_f32 v228, v76, v77
	v_cvt_pk_bf16_f32 v229, v78, v79
	v_cvt_pk_bf16_f32 v230, v68, v69
	v_cvt_pk_bf16_f32 v231, v70, v71
	global_store_dwordx4 v[234:235], v[228:231], off
	v_pk_mul_f32 v[206:207], v[60:61], v[60:61]
	v_pk_mul_f32 v[208:209], v[62:63], v[62:63]
	v_pk_mul_f32 v[210:211], v[52:53], v[52:53]
	v_pk_mul_f32 v[212:213], v[54:55], v[54:55]
	v_pk_fma_f32 v[206:207], v[206:207], s[100:101], v[204:205] op_sel_hi:[1,0,0]
	v_pk_fma_f32 v[208:209], v[208:209], s[100:101], v[204:205] op_sel_hi:[1,0,0]
	v_pk_fma_f32 v[210:211], v[210:211], s[100:101], v[204:205] op_sel_hi:[1,0,0]
	v_pk_fma_f32 v[212:213], v[212:213], s[100:101], v[204:205] op_sel_hi:[1,0,0]
	v_pk_mul_f32 v[206:207], v[60:61], v[206:207]
	v_pk_mul_f32 v[208:209], v[62:63], v[208:209]
	v_pk_mul_f32 v[210:211], v[52:53], v[210:211]
	v_pk_mul_f32 v[212:213], v[54:55], v[212:213]
	v_pk_mul_f32 v[214:215], v[56:57], s[100:101] op_sel:[0,1] op_sel_hi:[1,1]
	v_pk_mul_f32 v[216:217], v[58:59], s[100:101] op_sel:[0,1] op_sel_hi:[1,1]
	v_pk_mul_f32 v[218:219], v[48:49], s[100:101] op_sel:[0,1] op_sel_hi:[1,1]
	v_pk_mul_f32 v[220:221], v[50:51], s[100:101] op_sel:[0,1] op_sel_hi:[1,1]
	v_pk_mul_f32 v[60:61], v[60:61], v[56:57]
	v_pk_mul_f32 v[62:63], v[62:63], v[58:59]
	v_pk_mul_f32 v[52:53], v[52:53], v[48:49]
	v_pk_mul_f32 v[54:55], v[54:55], v[50:51]
	v_exp_f32_e32 v206, v206
	v_exp_f32_e32 v207, v207
	v_exp_f32_e32 v208, v208
	v_exp_f32_e32 v209, v209
	v_exp_f32_e32 v210, v210
	v_exp_f32_e32 v211, v211
	v_exp_f32_e32 v212, v212
	v_exp_f32_e32 v213, v213
	v_exp_f32_e32 v214, v214
	v_exp_f32_e32 v215, v215
	v_exp_f32_e32 v216, v216
	v_exp_f32_e32 v217, v217
	v_exp_f32_e32 v218, v218
	v_exp_f32_e32 v219, v219
	v_exp_f32_e32 v220, v220
	v_exp_f32_e32 v221, v221
	v_pk_add_f32 v[206:207], v[206:207], 1.0 op_sel_hi:[1,0]
	v_pk_add_f32 v[208:209], v[208:209], 1.0 op_sel_hi:[1,0]
	v_pk_add_f32 v[210:211], v[210:211], 1.0 op_sel_hi:[1,0]
	v_pk_add_f32 v[212:213], v[212:213], 1.0 op_sel_hi:[1,0]
	v_pk_add_f32 v[214:215], v[214:215], 1.0 op_sel_hi:[1,0]
	v_pk_add_f32 v[216:217], v[216:217], 1.0 op_sel_hi:[1,0]
	v_pk_add_f32 v[218:219], v[218:219], 1.0 op_sel_hi:[1,0]
	v_pk_add_f32 v[220:221], v[220:221], 1.0 op_sel_hi:[1,0]
	v_pk_mul_f32 v[206:207], v[206:207], v[214:215]
	v_pk_mul_f32 v[208:209], v[208:209], v[216:217]
	v_pk_mul_f32 v[210:211], v[210:211], v[218:219]
	v_pk_mul_f32 v[212:213], v[212:213], v[220:221]
	v_rcp_f32_e32 v206, v206
	v_rcp_f32_e32 v207, v207
	v_rcp_f32_e32 v208, v208
	v_rcp_f32_e32 v209, v209
	v_rcp_f32_e32 v210, v210
	v_rcp_f32_e32 v211, v211
	v_rcp_f32_e32 v212, v212
	v_rcp_f32_e32 v213, v213
	s_mov_b32 s98, 0x100000
	v_lshl_add_u64 v[236:237], v[232:233], 0, s[98:99]
	v_pk_mul_f32 v[60:61], v[60:61], v[206:207]
	v_pk_mul_f32 v[62:63], v[62:63], v[208:209]
	v_pk_mul_f32 v[52:53], v[52:53], v[210:211]
	v_pk_mul_f32 v[54:55], v[54:55], v[212:213]
	v_cvt_pk_bf16_f32 v224, v60, v61
	v_cvt_pk_bf16_f32 v225, v62, v63
	v_cvt_pk_bf16_f32 v226, v52, v53
	v_cvt_pk_bf16_f32 v227, v54, v55
	global_store_dwordx4 v[236:237], v[224:227], off
	v_pk_mul_f32 v[206:207], v[44:45], v[44:45]
	v_pk_mul_f32 v[208:209], v[46:47], v[46:47]
	v_pk_mul_f32 v[210:211], v[36:37], v[36:37]
	v_pk_mul_f32 v[212:213], v[38:39], v[38:39]
	v_pk_fma_f32 v[206:207], v[206:207], s[100:101], v[204:205] op_sel_hi:[1,0,0]
	v_pk_fma_f32 v[208:209], v[208:209], s[100:101], v[204:205] op_sel_hi:[1,0,0]
	v_pk_fma_f32 v[210:211], v[210:211], s[100:101], v[204:205] op_sel_hi:[1,0,0]
	v_pk_fma_f32 v[212:213], v[212:213], s[100:101], v[204:205] op_sel_hi:[1,0,0]
	v_pk_mul_f32 v[206:207], v[44:45], v[206:207]
	v_pk_mul_f32 v[208:209], v[46:47], v[208:209]
	v_pk_mul_f32 v[210:211], v[36:37], v[210:211]
	v_pk_mul_f32 v[212:213], v[38:39], v[212:213]
	v_pk_mul_f32 v[214:215], v[40:41], s[100:101] op_sel:[0,1] op_sel_hi:[1,1]
	v_pk_mul_f32 v[216:217], v[42:43], s[100:101] op_sel:[0,1] op_sel_hi:[1,1]
	v_pk_mul_f32 v[218:219], v[32:33], s[100:101] op_sel:[0,1] op_sel_hi:[1,1]
	v_pk_mul_f32 v[220:221], v[34:35], s[100:101] op_sel:[0,1] op_sel_hi:[1,1]
	v_pk_mul_f32 v[44:45], v[44:45], v[40:41]
	v_pk_mul_f32 v[46:47], v[46:47], v[42:43]
	v_pk_mul_f32 v[36:37], v[36:37], v[32:33]
	v_pk_mul_f32 v[38:39], v[38:39], v[34:35]
	v_exp_f32_e32 v206, v206
	v_exp_f32_e32 v207, v207
	v_exp_f32_e32 v208, v208
	v_exp_f32_e32 v209, v209
	v_exp_f32_e32 v210, v210
	v_exp_f32_e32 v211, v211
	v_exp_f32_e32 v212, v212
	v_exp_f32_e32 v213, v213
	v_exp_f32_e32 v214, v214
	v_exp_f32_e32 v215, v215
	v_exp_f32_e32 v216, v216
	v_exp_f32_e32 v217, v217
	v_exp_f32_e32 v218, v218
	v_exp_f32_e32 v219, v219
	v_exp_f32_e32 v220, v220
	v_exp_f32_e32 v221, v221
	v_pk_add_f32 v[206:207], v[206:207], 1.0 op_sel_hi:[1,0]
	v_pk_add_f32 v[208:209], v[208:209], 1.0 op_sel_hi:[1,0]
	v_pk_add_f32 v[210:211], v[210:211], 1.0 op_sel_hi:[1,0]
	v_pk_add_f32 v[212:213], v[212:213], 1.0 op_sel_hi:[1,0]
	v_pk_add_f32 v[214:215], v[214:215], 1.0 op_sel_hi:[1,0]
	v_pk_add_f32 v[216:217], v[216:217], 1.0 op_sel_hi:[1,0]
	v_pk_add_f32 v[218:219], v[218:219], 1.0 op_sel_hi:[1,0]
; __device__ __forceinline__ unsigned cvt_pk_bf16(float lo, float hi) { unsigned r; asm volatile("v_cvt_pk_bf16_f32 %0, %1, %2" : "=v"(r) : "v"(lo), "v"(hi)); return r; }
; __device__ __forceinline__ float gelu_silu(float u, float z) {
;     const float e1 = __builtin_amdgcn_exp2f(u * __builtin_fmaf(u * u, GELU_C2, GELU_C1));
;     const float e2 = __builtin_amdgcn_exp2f(z * -LOG2E);
;     return (u * z) * __builtin_amdgcn_rcpf((1.0f + e1) * (1.0f + e2));
; }
;     __device__ __forceinline__ void operator()(const f32x4 (&acc)[2][2][4][2], const Unit& u, int wr, int wc, int fr, int fq) const {
;     ...
; #pragma unroll
;             for (int ai = 0; ai < 2; ++ai)
; #pragma unroll
;                 for (int m = 0; m < 4; ++m) {
;                     const int row = row0 + ai * HALF + m * 16;
;                     f32x4 v0 = acc[ai][0][m][0], v1 = acc[ai][0][m][1]; const f32x4 z0 = acc[ai][1][m][0], z1 = acc[ai][1][m][1];
; #pragma unroll
;                     for (int e = 0; e < 4; ++e) { v0[e] = gelu_silu(v0[e], z0[e]); v1[e] = gelu_silu(v1[e], z1[e]); }
;                     u32x4 w; w.x = cvt_pk_bf16(v0[0], v0[1]); w.y = cvt_pk_bf16(v0[2], v0[3]); w.z = cvt_pk_bf16(v1[0], v1[1]); w.w = cvt_pk_bf16(v1[2], v1[3]);
;                     *(u32x4*)(UZ + (size_t)row * GW + col0) = w;
;                 }
	v_pk_add_f32 v[220:221], v[220:221], 1.0 op_sel_hi:[1,0]
	v_pk_mul_f32 v[206:207], v[206:207], v[214:215]
	v_pk_mul_f32 v[208:209], v[208:209], v[216:217]
	v_pk_mul_f32 v[210:211], v[210:211], v[218:219]
	v_pk_mul_f32 v[212:213], v[212:213], v[220:221]
	v_rcp_f32_e32 v206, v206
	v_rcp_f32_e32 v207, v207
	v_rcp_f32_e32 v208, v208
	v_rcp_f32_e32 v209, v209
	v_rcp_f32_e32 v210, v210
	v_rcp_f32_e32 v211, v211
	v_rcp_f32_e32 v212, v212
	v_rcp_f32_e32 v213, v213
	s_mov_b32 s98, 0x120000
	v_lshl_add_u64 v[234:235], v[232:233], 0, s[98:99]
	v_pk_mul_f32 v[44:45], v[44:45], v[206:207]
	v_pk_mul_f32 v[46:47], v[46:47], v[208:209]
	v_pk_mul_f32 v[36:37], v[36:37], v[210:211]
	v_pk_mul_f32 v[38:39], v[38:39], v[212:213]
	v_cvt_pk_bf16_f32 v228, v44, v45
	v_cvt_pk_bf16_f32 v229, v46, v47
	v_cvt_pk_bf16_f32 v230, v36, v37
	v_cvt_pk_bf16_f32 v231, v38, v39
	global_store_dwordx4 v[234:235], v[228:231], off
	v_pk_mul_f32 v[206:207], v[28:29], v[28:29]
	v_pk_mul_f32 v[208:209], v[30:31], v[30:31]
	v_pk_mul_f32 v[210:211], v[20:21], v[20:21]
	v_pk_mul_f32 v[212:213], v[22:23], v[22:23]
	v_pk_fma_f32 v[206:207], v[206:207], s[100:101], v[204:205] op_sel_hi:[1,0,0]
	v_pk_fma_f32 v[208:209], v[208:209], s[100:101], v[204:205] op_sel_hi:[1,0,0]
	v_pk_fma_f32 v[210:211], v[210:211], s[100:101], v[204:205] op_sel_hi:[1,0,0]
	v_pk_fma_f32 v[212:213], v[212:213], s[100:101], v[204:205] op_sel_hi:[1,0,0]
	v_pk_mul_f32 v[206:207], v[28:29], v[206:207]
	v_pk_mul_f32 v[208:209], v[30:31], v[208:209]
	v_pk_mul_f32 v[210:211], v[20:21], v[210:211]
	v_pk_mul_f32 v[212:213], v[22:23], v[212:213]
	v_pk_mul_f32 v[214:215], v[24:25], s[100:101] op_sel:[0,1] op_sel_hi:[1,1]
	v_pk_mul_f32 v[216:217], v[26:27], s[100:101] op_sel:[0,1] op_sel_hi:[1,1]
	v_pk_mul_f32 v[218:219], v[16:17], s[100:101] op_sel:[0,1] op_sel_hi:[1,1]
	v_pk_mul_f32 v[220:221], v[18:19], s[100:101] op_sel:[0,1] op_sel_hi:[1,1]
	v_pk_mul_f32 v[28:29], v[28:29], v[24:25]
	v_pk_mul_f32 v[30:31], v[30:31], v[26:27]
	v_pk_mul_f32 v[20:21], v[20:21], v[16:17]
	v_pk_mul_f32 v[22:23], v[22:23], v[18:19]
	v_exp_f32_e32 v206, v206
	v_exp_f32_e32 v207, v207
	v_exp_f32_e32 v208, v208
	v_exp_f32_e32 v209, v209
	v_exp_f32_e32 v210, v210
	v_exp_f32_e32 v211, v211
	v_exp_f32_e32 v212, v212
	v_exp_f32_e32 v213, v213
	v_exp_f32_e32 v214, v214
	v_exp_f32_e32 v215, v215
	v_exp_f32_e32 v216, v216
	v_exp_f32_e32 v217, v217
	v_exp_f32_e32 v218, v218
	v_exp_f32_e32 v219, v219
	v_exp_f32_e32 v220, v220
	v_exp_f32_e32 v221, v221
	v_pk_add_f32 v[206:207], v[206:207], 1.0 op_sel_hi:[1,0]
	v_pk_add_f32 v[208:209], v[208:209], 1.0 op_sel_hi:[1,0]
	v_pk_add_f32 v[210:211], v[210:211], 1.0 op_sel_hi:[1,0]
	v_pk_add_f32 v[212:213], v[212:213], 1.0 op_sel_hi:[1,0]
	v_pk_add_f32 v[214:215], v[214:215], 1.0 op_sel_hi:[1,0]
	v_pk_add_f32 v[216:217], v[216:217], 1.0 op_sel_hi:[1,0]
	v_pk_add_f32 v[218:219], v[218:219], 1.0 op_sel_hi:[1,0]
	v_pk_add_f32 v[220:221], v[220:221], 1.0 op_sel_hi:[1,0]
	v_pk_mul_f32 v[206:207], v[206:207], v[214:215]
	v_pk_mul_f32 v[208:209], v[208:209], v[216:217]
	v_pk_mul_f32 v[210:211], v[210:211], v[218:219]
	v_pk_mul_f32 v[212:213], v[212:213], v[220:221]
	v_rcp_f32_e32 v206, v206
	v_rcp_f32_e32 v207, v207
	v_rcp_f32_e32 v208, v208
	v_rcp_f32_e32 v209, v209
	v_rcp_f32_e32 v210, v210
	v_rcp_f32_e32 v211, v211
	v_rcp_f32_e32 v212, v212
	v_rcp_f32_e32 v213, v213
	s_mov_b32 s98, 0x140000
	v_lshl_add_u64 v[236:237], v[232:233], 0, s[98:99]
	v_pk_mul_f32 v[28:29], v[28:29], v[206:207]
	v_pk_mul_f32 v[30:31], v[30:31], v[208:209]
	v_pk_mul_f32 v[20:21], v[20:21], v[210:211]
	v_pk_mul_f32 v[22:23], v[22:23], v[212:213]
	v_cvt_pk_bf16_f32 v224, v28, v29
	v_cvt_pk_bf16_f32 v225, v30, v31
	v_cvt_pk_bf16_f32 v226, v20, v21
	v_cvt_pk_bf16_f32 v227, v22, v23
	global_store_dwordx4 v[236:237], v[224:227], off
	v_pk_mul_f32 v[206:207], v[12:13], v[12:13]
	v_pk_mul_f32 v[208:209], v[14:15], v[14:15]
	v_pk_mul_f32 v[210:211], v[4:5], v[4:5]
	v_pk_mul_f32 v[212:213], v[6:7], v[6:7]
	v_pk_fma_f32 v[206:207], v[206:207], s[100:101], v[204:205] op_sel_hi:[1,0,0]
	v_pk_fma_f32 v[208:209], v[208:209], s[100:101], v[204:205] op_sel_hi:[1,0,0]
	v_pk_fma_f32 v[210:211], v[210:211], s[100:101], v[204:205] op_sel_hi:[1,0,0]
	v_pk_fma_f32 v[212:213], v[212:213], s[100:101], v[204:205] op_sel_hi:[1,0,0]
	v_pk_mul_f32 v[206:207], v[12:13], v[206:207]
	v_pk_mul_f32 v[208:209], v[14:15], v[208:209]
	v_pk_mul_f32 v[210:211], v[4:5], v[210:211]
	v_pk_mul_f32 v[212:213], v[6:7], v[212:213]
	v_pk_mul_f32 v[214:215], v[8:9], s[100:101] op_sel:[0,1] op_sel_hi:[1,1]
	v_pk_mul_f32 v[216:217], v[10:11], s[100:101] op_sel:[0,1] op_sel_hi:[1,1]
	v_pk_mul_f32 v[218:219], v[0:1], s[100:101] op_sel:[0,1] op_sel_hi:[1,1]
	v_pk_mul_f32 v[220:221], v[2:3], s[100:101] op_sel:[0,1] op_sel_hi:[1,1]
	v_pk_mul_f32 v[12:13], v[12:13], v[8:9]
	v_pk_mul_f32 v[14:15], v[14:15], v[10:11]
	v_pk_mul_f32 v[4:5], v[4:5], v[0:1]
	v_pk_mul_f32 v[6:7], v[6:7], v[2:3]
	v_exp_f32_e32 v206, v206
	v_exp_f32_e32 v207, v207
	v_exp_f32_e32 v208, v208
	v_exp_f32_e32 v209, v209
	v_exp_f32_e32 v210, v210
	v_exp_f32_e32 v211, v211
	v_exp_f32_e32 v212, v212
	v_exp_f32_e32 v213, v213
	v_exp_f32_e32 v214, v214
	v_exp_f32_e32 v215, v215
	v_exp_f32_e32 v216, v216
	v_exp_f32_e32 v217, v217
	v_exp_f32_e32 v218, v218
	v_exp_f32_e32 v219, v219
	v_exp_f32_e32 v220, v220
	v_exp_f32_e32 v221, v221
	v_pk_add_f32 v[206:207], v[206:207], 1.0 op_sel_hi:[1,0]
	v_pk_add_f32 v[208:209], v[208:209], 1.0 op_sel_hi:[1,0]
	v_pk_add_f32 v[210:211], v[210:211], 1.0 op_sel_hi:[1,0]
	v_pk_add_f32 v[212:213], v[212:213], 1.0 op_sel_hi:[1,0]
	v_pk_add_f32 v[214:215], v[214:215], 1.0 op_sel_hi:[1,0]
	v_pk_add_f32 v[216:217], v[216:217], 1.0 op_sel_hi:[1,0]
	v_pk_add_f32 v[218:219], v[218:219], 1.0 op_sel_hi:[1,0]
	v_pk_add_f32 v[220:221], v[220:221], 1.0 op_sel_hi:[1,0]
	v_pk_mul_f32 v[206:207], v[206:207], v[214:215]
	v_pk_mul_f32 v[208:209], v[208:209], v[216:217]
	v_pk_mul_f32 v[210:211], v[210:211], v[218:219]
	v_pk_mul_f32 v[212:213], v[212:213], v[220:221]
	v_rcp_f32_e32 v206, v206
	v_rcp_f32_e32 v207, v207
	v_rcp_f32_e32 v208, v208
	v_rcp_f32_e32 v209, v209
	v_rcp_f32_e32 v210, v210
	v_rcp_f32_e32 v211, v211
	v_rcp_f32_e32 v212, v212
	v_rcp_f32_e32 v213, v213
	s_mov_b32 s98, 0x160000
	v_lshl_add_u64 v[234:235], v[232:233], 0, s[98:99]
	v_pk_mul_f32 v[12:13], v[12:13], v[206:207]
	v_pk_mul_f32 v[14:15], v[14:15], v[208:209]
	v_pk_mul_f32 v[4:5], v[4:5], v[210:211]
	v_pk_mul_f32 v[6:7], v[6:7], v[212:213]
	v_cvt_pk_bf16_f32 v228, v12, v13
	v_cvt_pk_bf16_f32 v229, v14, v15
	v_cvt_pk_bf16_f32 v230, v4, v5
	v_cvt_pk_bf16_f32 v231, v6, v7
	global_store_dwordx4 v[234:235], v[228:231], off
	s_cmp_lg_u32 s45, s59
	s_cbranch_scc1 .LBB0_203

; #define LAS __attribute__((address_space(3)))
; __device__ __forceinline__ s16x4 vtr(const LAS unsigned char* p) { return __builtin_bit_cast(s16x4, __builtin_amdgcn_ds_read_tr16_b64_v4i16((LAS s16x4*)p)); }
; __device__ __forceinline__ int crow(int r, int hi) { return (r & 3) + 8 * (r >> 2) + 4 * hi; }
; #define lane lane_id()
; __device__ __forceinline__ void mix_unit(LAS unsigned char* lds, const int wid, int n, int g, const bf16_t* __restrict__ UZ, const bf16_t* __restrict__ V, const float* __restrict__ vss, ...
;     ...
;         const LAS unsigned char* vimg = lds + 32768 + (wid >> 2) * 32768;
;         const unsigned cblk = wid & 3, qa = (lane & 15) >> 2, blk = (lane >> 4) & 1, pp = lane & 3;
; #pragma unroll
;         for (int ks = 0; ks < 8; ++ks) {
;             const s16x4 lo = vtr(vimg + off_b(16 * ks + 8 * hi + qa, 4 * cblk + 2 * blk + (pp >> 1)) + 8 * (pp & 1));
;             const s16x4 hh = vtr(vimg + off_b(16 * ks + 8 * hi + 4 + qa, 4 * cblk + 2 * blk + (pp >> 1)) + 8 * (pp & 1));
;             const bf16x8 vf = (bf16x8){lo[0], lo[1], lo[2], lo[3], hh[0], hh[1], hh[2], hh[3]};
; #pragma unroll
;             for (int i = 0; i < 4; ++i) if (ks <= 2 * i + 1) {
;                 const bf16x8 af = *(const LAS bf16x8*)(lds + off_b(32 * i + r32, 2 * ks + hi));
;                 acc[i] = __builtin_amdgcn_mfma_f32_32x32x16_bf16(af, vf, acc[i], 0, 0, 0);
;             }
;         }
;     }
;     __syncthreads();
;     {
;         LAS float* mx = (LAS float*)lds;
;         const int c = 128 * (wid >> 2) + 32 * (wid & 3) + r32;
; #pragma unroll
;         for (int i = 0; i < 4; ++i)
; #pragma unroll
;             for (int r = 0; r < 16; ++r) mx[(32 * i + crow(r, hi)) * 256 + c] = acc[i][r];
;     }
.Lp2_mfma:
	ds_read_b64_tr_b16 v[0:1], v218 offset:32768
	ds_read_b64_tr_b16 v[2:3], v219 offset:33792
	ds_read_b128 v[4:7], v220
	s_waitcnt lgkmcnt(0)
	v_mfma_f32_32x32x16_bf16 v[48:63], v[4:7], v[0:3], 0
	ds_read_b128 v[4:7], v220 offset:8192
	s_lshl_b32 s72, s97, 8
	s_lshl_b32 s82, s72, 2
	s_mov_b32 s83, s77
	s_waitcnt lgkmcnt(0)
	v_mfma_f32_32x32x16_bf16 v[32:47], v[4:7], v[0:3], 0
	ds_read_b128 v[4:7], v220 offset:16384
	s_waitcnt lgkmcnt(0)
	v_mfma_f32_32x32x16_bf16 v[16:31], v[4:7], v[0:3], 0
	ds_read_b128 v[4:7], v220 offset:24576
	ds_read_b64_tr_b16 v[236:237], v218 offset:36864
	ds_read_b64_tr_b16 v[238:239], v219 offset:37888
	ds_read_b128 v[240:243], v221
	s_waitcnt lgkmcnt(0)
	v_mfma_f32_32x32x16_bf16 v[48:63], v[240:243], v[236:239], v[48:63]
	ds_read_b128 v[240:243], v221 offset:8192
	s_waitcnt lgkmcnt(0)
	v_mfma_f32_32x32x16_bf16 v[32:47], v[240:243], v[236:239], v[32:47]
	ds_read_b128 v[240:243], v221 offset:16384
	s_waitcnt lgkmcnt(0)
	v_mfma_f32_32x32x16_bf16 v[16:31], v[240:243], v[236:239], v[16:31]
	ds_read_b128 v[240:243], v221 offset:24576
	v_mfma_f32_32x32x16_bf16 v[0:15], v[4:7], v[0:3], 0
	s_waitcnt lgkmcnt(0)
	v_mfma_f32_32x32x16_bf16 v[0:15], v[240:243], v[236:239], v[0:15]
	ds_read_b64_tr_b16 v[236:237], v218 offset:40960
	ds_read_b64_tr_b16 v[238:239], v219 offset:41984
	ds_read_b128 v[240:243], v222 offset:8192
	s_waitcnt lgkmcnt(0)
	v_mfma_f32_32x32x16_bf16 v[32:47], v[240:243], v[236:239], v[32:47]
	ds_read_b128 v[240:243], v222 offset:16384
	s_waitcnt lgkmcnt(0)
	v_mfma_f32_32x32x16_bf16 v[16:31], v[240:243], v[236:239], v[16:31]
	ds_read_b128 v[240:243], v222 offset:24576
	s_waitcnt lgkmcnt(0)
	v_mfma_f32_32x32x16_bf16 v[0:15], v[240:243], v[236:239], v[0:15]
	ds_read_b64_tr_b16 v[236:237], v218 offset:45056
	ds_read_b64_tr_b16 v[238:239], v219 offset:46080
	ds_read_b128 v[240:243], v223 offset:8192
	s_waitcnt lgkmcnt(0)
	v_mfma_f32_32x32x16_bf16 v[32:47], v[240:243], v[236:239], v[32:47]
	ds_read_b128 v[240:243], v223 offset:16384
	s_waitcnt lgkmcnt(0)
	v_mfma_f32_32x32x16_bf16 v[16:31], v[240:243], v[236:239], v[16:31]
	ds_read_b128 v[240:243], v223 offset:24576
	s_waitcnt lgkmcnt(0)
	v_mfma_f32_32x32x16_bf16 v[0:15], v[240:243], v[236:239], v[0:15]
	ds_read_b64_tr_b16 v[236:237], v218 offset:49152
	ds_read_b64_tr_b16 v[238:239], v219 offset:50176
	ds_read_b128 v[240:243], v224 offset:16384
	s_waitcnt lgkmcnt(0)
	v_mfma_f32_32x32x16_bf16 v[16:31], v[240:243], v[236:239], v[16:31]
	ds_read_b128 v[240:243], v224 offset:24576
	s_waitcnt lgkmcnt(0)
	v_mfma_f32_32x32x16_bf16 v[0:15], v[240:243], v[236:239], v[0:15]
	ds_read_b64_tr_b16 v[236:237], v218 offset:53248
	ds_read_b64_tr_b16 v[238:239], v219 offset:54272
	ds_read_b128 v[240:243], v225 offset:16384
	s_waitcnt lgkmcnt(0)
	v_mfma_f32_32x32x16_bf16 v[16:31], v[240:243], v[236:239], v[16:31]
	ds_read_b128 v[240:243], v225 offset:24576
	s_waitcnt lgkmcnt(0)
	v_mfma_f32_32x32x16_bf16 v[0:15], v[240:243], v[236:239], v[0:15]
	ds_read_b64_tr_b16 v[236:237], v218 offset:57344
	ds_read_b64_tr_b16 v[238:239], v219 offset:58368
	ds_read_b128 v[240:243], v226 offset:24576
	s_waitcnt lgkmcnt(0)
	v_mfma_f32_32x32x16_bf16 v[0:15], v[240:243], v[236:239], v[0:15]
	ds_read_b64_tr_b16 v[236:237], v218 offset:61440
	ds_read_b64_tr_b16 v[238:239], v219 offset:62464
	ds_read_b128 v[240:243], v227 offset:24576
	s_waitcnt lgkmcnt(0)
	s_barrier
	v_mfma_f32_32x32x16_bf16 v[0:15], v[240:243], v[236:239], v[0:15]
	ds_write2st64_b32 v171, v48, v49 offset1:4
	ds_write2st64_b32 v171, v50, v51 offset0:8 offset1:12
	ds_write2st64_b32 v171, v52, v53 offset0:32 offset1:36
	ds_write2st64_b32 v171, v54, v55 offset0:40 offset1:44
	ds_write2st64_b32 v171, v56, v57 offset0:64 offset1:68
	ds_write2st64_b32 v171, v58, v59 offset0:72 offset1:76
	ds_write2st64_b32 v171, v60, v61 offset0:96 offset1:100
	ds_write2st64_b32 v171, v62, v63 offset0:104 offset1:108
	ds_write2st64_b32 v171, v32, v33 offset0:128 offset1:132
	ds_write2st64_b32 v171, v34, v35 offset0:136 offset1:140
	ds_write2st64_b32 v171, v36, v37 offset0:160 offset1:164
	ds_write2st64_b32 v171, v38, v39 offset0:168 offset1:172
	ds_write2st64_b32 v171, v40, v41 offset0:192 offset1:196
	ds_write2st64_b32 v171, v42, v43 offset0:200 offset1:204
	ds_write2st64_b32 v171, v44, v45 offset0:224 offset1:228
	ds_write2st64_b32 v171, v46, v47 offset0:232 offset1:236
	ds_write_b32 v172, v16
	ds_write_b32 v173, v17
	ds_write_b32 v174, v18
	ds_write_b32 v175, v19
	ds_write_b32 v176, v20
	ds_write_b32 v177, v21
	ds_write_b32 v178, v22
	ds_write_b32 v179, v23
	ds_write_b32 v180, v24
	ds_write_b32 v181, v25
	ds_write_b32 v182, v26
	ds_write_b32 v183, v27
	ds_write_b32 v184, v28
	ds_write_b32 v185, v29
	ds_write_b32 v186, v30
	ds_write_b32 v187, v31
	ds_write_b32 v188, v0
	ds_write_b32 v189, v1
	ds_write_b32 v190, v2
	ds_write_b32 v191, v3
	ds_write_b32 v192, v4
	ds_write_b32 v193, v5
	ds_write_b32 v194, v6
	ds_write_b32 v196, v7
	ds_write_b32 v197, v8
	ds_write_b32 v198, v9
	ds_write_b32 v199, v10
	ds_write_b32 v200, v11
	ds_write_b32 v201, v12
	ds_write_b32 v202, v13
	ds_write_b32 v203, v14
	ds_write_b32 v204, v15
	v_lshl_add_u64 v[4:5], v[142:143], 0, s[82:83]
	s_waitcnt lgkmcnt(0)
	s_barrier
; #define LAS __attribute__((address_space(3)))
; __device__ __forceinline__ unsigned pk_bf16(float lo, float hi) { return pg8::cvt_pk_bf16(lo, hi); }
; __device__ __forceinline__ float bf_lo(unsigned w) { return __uint_as_float(w << 16); }
; __device__ __forceinline__ float bf_hi(unsigned w) { return __uint_as_float(w & 0xffff0000u); }
; #define tid tid_of(wave)
; __device__ __forceinline__ void mix_unit(LAS unsigned char* lds, const int wid, int n, int g, const bf16_t* __restrict__ UZ, const bf16_t* __restrict__ V, const float* __restrict__ vss, ...
;     ...
;         const f32x4 g0 = *(const f32x4*)(vg + g * GDIM + cc * 8), g1 = *(const f32x4*)(vg + g * GDIM + cc * 8 + 4);
;         float bb[8];
; #pragma unroll
;         for (int i = 0; i < 8; ++i) bb[i] = b_s[g * CHUNK + (tid >> 5) + 16 * i];
; #pragma unroll
;         for (int i = 0; i < 8; ++i) { const int t = (tid >> 5) + 16 * i;
;             const f32x4 m0 = *(const LAS f32x4*)(lds + (t * 256 + cc * 8) * 4), m1 = *(const LAS f32x4*)(lds + (t * 256 + cc * 8 + 4) * 4);
;             float y[8];
;             y[0] = bf_lo(uu[i].x) * (m0[0] * g0[0] + bb[i]); y[1] = bf_hi(uu[i].x) * (m0[1] * g0[1] + bb[i]);
;             y[2] = bf_lo(uu[i].y) * (m0[2] * g0[2] + bb[i]); y[3] = bf_hi(uu[i].y) * (m0[3] * g0[3] + bb[i]);
;             y[4] = bf_lo(uu[i].z) * (m1[0] * g1[0] + bb[i]); y[5] = bf_hi(uu[i].z) * (m1[1] * g1[1] + bb[i]);
;             y[6] = bf_lo(uu[i].w) * (m1[2] * g1[2] + bb[i]); y[7] = bf_hi(uu[i].w) * (m1[3] * g1[3] + bb[i]);
;             u32x4 w; w.x = pk_bf16(y[0], y[1]); w.y = pk_bf16(y[2], y[3]); w.z = pk_bf16(y[4], y[5]); w.w = pk_bf16(y[6], y[7]);
;             *(u32x4*)(Y + (row0 + t) * GW + g * GDIM + cc * 8) = w; }
	s_waitcnt vmcnt(0)
	global_load_dwordx4 v[0:3], v[4:5], off offset:16
	s_nop 0
	global_load_dwordx4 v[4:7], v[4:5], off
	v_add_u32_e32 v8, s76, v96
	v_readlane_b32 s80, v248, 6
	v_ashrrev_i32_e32 v9, 31, v8
	v_readlane_b32 s90, v248, 16
	v_readlane_b32 s91, v248, 17
	v_lshlrev_b32_e32 v26, 16, v92
	s_lshl_b32 s76, s72, 1
	v_lshl_add_u64 v[8:9], v[8:9], 2, s[90:91]
	global_load_dword v18, v[8:9], off
	global_load_dword v19, v[8:9], off offset:64
	global_load_dword v20, v[8:9], off offset:128
	global_load_dword v21, v[8:9], off offset:192
	global_load_dword v22, v[8:9], off offset:256
	global_load_dword v23, v[8:9], off offset:320
	global_load_dword v24, v[8:9], off offset:384
	global_load_dword v25, v[8:9], off offset:448
	ds_read_b128 v[10:13], v228
	ds_read_b128 v[14:17], v228 offset:16
	v_lshl_add_u64 v[8:9], v[144:145], 0, s[76:77]
	v_readlane_b32 s88, v248, 14
	v_readlane_b32 s89, v248, 15
	v_readlane_b32 s88, v248, 35
	s_add_i32 s71, s71, s88
	v_readlane_b32 s89, v248, 36
	s_cmpk_lt_i32 s71, 0x400
	v_readlane_b32 s81, v248, 7
	v_readlane_b32 s82, v248, 8
	v_readlane_b32 s83, v248, 9
	v_readlane_b32 s84, v248, 10
	v_readlane_b32 s85, v248, 11
	v_readlane_b32 s86, v248, 12
	v_readlane_b32 s87, v248, 13
	v_readlane_b32 s92, v248, 18
	v_readlane_b32 s93, v248, 19
	v_readlane_b32 s94, v248, 20
	v_readlane_b32 s95, v248, 21
	s_waitcnt vmcnt(7) lgkmcnt(0)
	v_fma_f32 v14, v0, v14, v18
	v_fma_f32 v10, v4, v10, v18
	v_mul_f32_e32 v10, v10, v26
	v_and_b32_e32 v26, 0xffff0000, v92
	v_fma_f32 v11, v5, v11, v18
	v_mul_f32_e32 v11, v11, v26
	v_lshlrev_b32_e32 v26, 16, v93
	v_fma_f32 v12, v6, v12, v18
	v_mul_f32_e32 v12, v12, v26
	v_and_b32_e32 v26, 0xffff0000, v93
	v_fma_f32 v13, v7, v13, v18
	v_mul_f32_e32 v13, v13, v26
	v_lshlrev_b32_e32 v26, 16, v94
	v_mul_f32_e32 v14, v14, v26
	v_and_b32_e32 v26, 0xffff0000, v94
	v_fma_f32 v15, v1, v15, v18
	v_mul_f32_e32 v15, v15, v26
	v_lshlrev_b32_e32 v26, 16, v95
	v_fma_f32 v16, v2, v16, v18
	v_mul_f32_e32 v16, v16, v26
	v_and_b32_e32 v26, 0xffff0000, v95
	v_fmac_f32_e32 v18, v3, v17
	v_cvt_pk_bf16_f32 v10, v10, v11
	v_cvt_pk_bf16_f32 v11, v12, v13
	v_cvt_pk_bf16_f32 v12, v14, v15
	v_lshl_add_u64 v[14:15], v[8:9], 0, v[162:163]
	v_mul_f32_e32 v17, v18, v26
	v_cvt_pk_bf16_f32 v13, v16, v17
	global_store_dwordx4 v[14:15], v[10:13], off
	ds_read_b128 v[10:13], v229
	ds_read_b128 v[14:17], v229 offset:16
	v_lshlrev_b32_e32 v18, 16, v88
	s_waitcnt vmcnt(7) lgkmcnt(1)
	v_fma_f32 v10, v4, v10, v19
	v_mul_f32_e32 v10, v10, v18
	v_and_b32_e32 v18, 0xffff0000, v88
	v_fma_f32 v11, v5, v11, v19
	v_mul_f32_e32 v11, v11, v18
	v_lshlrev_b32_e32 v18, 16, v89
	v_fma_f32 v12, v6, v12, v19
	v_mul_f32_e32 v12, v12, v18
	v_and_b32_e32 v18, 0xffff0000, v89
	v_fma_f32 v13, v7, v13, v19
	v_mul_f32_e32 v13, v13, v18
	v_lshlrev_b32_e32 v18, 16, v90
	s_waitcnt lgkmcnt(0)
	v_fma_f32 v14, v0, v14, v19
	v_mul_f32_e32 v14, v14, v18
	v_and_b32_e32 v18, 0xffff0000, v90
	v_fma_f32 v15, v1, v15, v19
	v_mul_f32_e32 v15, v15, v18
	v_lshlrev_b32_e32 v18, 16, v91
	v_fma_f32 v16, v2, v16, v19
	v_mul_f32_e32 v16, v16, v18
	v_and_b32_e32 v18, 0xffff0000, v91
	v_fmac_f32_e32 v19, v3, v17
	v_cvt_pk_bf16_f32 v10, v10, v11
	v_cvt_pk_bf16_f32 v11, v12, v13
	v_cvt_pk_bf16_f32 v12, v14, v15
	v_lshl_add_u64 v[14:15], v[8:9], 0, v[160:161]
	v_mul_f32_e32 v17, v19, v18
	v_cvt_pk_bf16_f32 v13, v16, v17
	global_store_dwordx4 v[14:15], v[10:13], off
	ds_read_b128 v[10:13], v230
	ds_read_b128 v[14:17], v230 offset:16
	v_lshlrev_b32_e32 v18, 16, v84
	s_waitcnt vmcnt(7) lgkmcnt(1)
	v_fma_f32 v10, v4, v10, v20
	v_mul_f32_e32 v10, v10, v18
	v_and_b32_e32 v18, 0xffff0000, v84
	v_fma_f32 v11, v5, v11, v20
	v_mul_f32_e32 v11, v11, v18
	v_lshlrev_b32_e32 v18, 16, v85
	v_fma_f32 v12, v6, v12, v20
	v_mul_f32_e32 v12, v12, v18
	v_and_b32_e32 v18, 0xffff0000, v85
	v_fma_f32 v13, v7, v13, v20
	v_mul_f32_e32 v13, v13, v18
	v_lshlrev_b32_e32 v18, 16, v86
	s_waitcnt lgkmcnt(0)
	v_fma_f32 v14, v0, v14, v20
	v_mul_f32_e32 v14, v14, v18
	v_and_b32_e32 v18, 0xffff0000, v86
	v_fma_f32 v15, v1, v15, v20
	v_mul_f32_e32 v15, v15, v18
	v_lshlrev_b32_e32 v18, 16, v87
	v_fma_f32 v16, v2, v16, v20
	v_mul_f32_e32 v16, v16, v18
	v_and_b32_e32 v18, 0xffff0000, v87
	v_fmac_f32_e32 v20, v3, v17
	v_cvt_pk_bf16_f32 v10, v10, v11
	v_cvt_pk_bf16_f32 v11, v12, v13
	v_cvt_pk_bf16_f32 v12, v14, v15
	v_lshl_add_u64 v[14:15], v[8:9], 0, v[158:159]
	v_mul_f32_e32 v17, v20, v18
	v_cvt_pk_bf16_f32 v13, v16, v17
	global_store_dwordx4 v[14:15], v[10:13], off
	ds_read_b128 v[10:13], v231
	ds_read_b128 v[14:17], v231 offset:16
	v_lshlrev_b32_e32 v18, 16, v80
	s_waitcnt vmcnt(7) lgkmcnt(1)
	v_fma_f32 v10, v4, v10, v21
	v_mul_f32_e32 v10, v10, v18
	v_and_b32_e32 v18, 0xffff0000, v80
	v_fma_f32 v11, v5, v11, v21
	v_mul_f32_e32 v11, v11, v18
	v_lshlrev_b32_e32 v18, 16, v81
	v_fma_f32 v12, v6, v12, v21
	v_mul_f32_e32 v12, v12, v18
	v_and_b32_e32 v18, 0xffff0000, v81
	v_fma_f32 v13, v7, v13, v21
	v_mul_f32_e32 v13, v13, v18
	v_lshlrev_b32_e32 v18, 16, v82
	s_waitcnt lgkmcnt(0)
	v_fma_f32 v14, v0, v14, v21
	v_mul_f32_e32 v14, v14, v18
	v_and_b32_e32 v18, 0xffff0000, v82
	v_fma_f32 v15, v1, v15, v21
	v_mul_f32_e32 v15, v15, v18
	v_lshlrev_b32_e32 v18, 16, v83
	v_fma_f32 v16, v2, v16, v21
	v_mul_f32_e32 v16, v16, v18
	v_and_b32_e32 v18, 0xffff0000, v83
	v_fmac_f32_e32 v21, v3, v17
	v_cvt_pk_bf16_f32 v10, v10, v11
	v_cvt_pk_bf16_f32 v11, v12, v13
	v_cvt_pk_bf16_f32 v12, v14, v15
	v_lshl_add_u64 v[14:15], v[8:9], 0, v[156:157]
	v_mul_f32_e32 v17, v21, v18
	v_cvt_pk_bf16_f32 v13, v16, v17
	global_store_dwordx4 v[14:15], v[10:13], off
	ds_read_b128 v[10:13], v232
	ds_read_b128 v[14:17], v232 offset:16
	v_lshlrev_b32_e32 v18, 16, v76
	s_waitcnt vmcnt(7) lgkmcnt(1)
; #define LAS __attribute__((address_space(3)))
; __device__ __forceinline__ unsigned pk_bf16(float lo, float hi) { return pg8::cvt_pk_bf16(lo, hi); }
; __device__ __forceinline__ float bf_lo(unsigned w) { return __uint_as_float(w << 16); }
; __device__ __forceinline__ float bf_hi(unsigned w) { return __uint_as_float(w & 0xffff0000u); }
; #define tid tid_of(wave)
; __device__ __forceinline__ void mix_unit(LAS unsigned char* lds, const int wid, int n, int g, const bf16_t* __restrict__ UZ, const bf16_t* __restrict__ V, const float* __restrict__ vss, ...
;     ...
;     u32x4 uu[8];
; #pragma unroll
;     for (int i = 0; i < 8; ++i) { const int t = (tid >> 5) + 16 * i; uu[i] = __builtin_nontemporal_load((const u32x4*)(UZ + (row0 + t) * GW + g * GDIM + cc * 8)); }
;     {
;         u32x4 vr[8];
; #pragma unroll
;         for (int i = 0; i < 8; ++i) { const int c = tid + 512 * i, s = c >> 5, cc = c & 31;
;             vr[i] = __builtin_nontemporal_load((const u32x4*)(V + (row0 + s) * GW + g * GDIM + cc * 8)); }
;         if (tid < 128) rstdL[tid] = __builtin_amdgcn_rsqf(vss[row0 + tid] * (1.0f / GW) + EPS);
;     ...
;         for (int i = 0; i < 8; ++i) { const int t = (tid >> 5) + 16 * i;
;             const f32x4 m0 = *(const LAS f32x4*)(lds + (t * 256 + cc * 8) * 4), m1 = *(const LAS f32x4*)(lds + (t * 256 + cc * 8 + 4) * 4);
;             float y[8];
;             y[0] = bf_lo(uu[i].x) * (m0[0] * g0[0] + bb[i]); y[1] = bf_hi(uu[i].x) * (m0[1] * g0[1] + bb[i]);
;             y[2] = bf_lo(uu[i].y) * (m0[2] * g0[2] + bb[i]); y[3] = bf_hi(uu[i].y) * (m0[3] * g0[3] + bb[i]);
;             y[4] = bf_lo(uu[i].z) * (m1[0] * g1[0] + bb[i]); y[5] = bf_hi(uu[i].z) * (m1[1] * g1[1] + bb[i]);
;             y[6] = bf_lo(uu[i].w) * (m1[2] * g1[2] + bb[i]); y[7] = bf_hi(uu[i].w) * (m1[3] * g1[3] + bb[i]);
;             u32x4 w; w.x = pk_bf16(y[0], y[1]); w.y = pk_bf16(y[2], y[3]); w.z = pk_bf16(y[4], y[5]); w.w = pk_bf16(y[6], y[7]);
;             *(u32x4*)(Y + (row0 + t) * GW + g * GDIM + cc * 8) = w; }
	v_fma_f32 v10, v4, v10, v22
	v_mul_f32_e32 v10, v10, v18
	v_and_b32_e32 v18, 0xffff0000, v76
	v_fma_f32 v11, v5, v11, v22
	v_mul_f32_e32 v11, v11, v18
	v_lshlrev_b32_e32 v18, 16, v77
	v_fma_f32 v12, v6, v12, v22
	v_mul_f32_e32 v12, v12, v18
	v_and_b32_e32 v18, 0xffff0000, v77
	v_fma_f32 v13, v7, v13, v22
	v_mul_f32_e32 v13, v13, v18
	v_lshlrev_b32_e32 v18, 16, v78
	s_waitcnt lgkmcnt(0)
	v_fma_f32 v14, v0, v14, v22
	v_mul_f32_e32 v14, v14, v18
	v_and_b32_e32 v18, 0xffff0000, v78
	v_fma_f32 v15, v1, v15, v22
	v_mul_f32_e32 v15, v15, v18
	v_lshlrev_b32_e32 v18, 16, v79
	v_fma_f32 v16, v2, v16, v22
	v_mul_f32_e32 v16, v16, v18
	v_and_b32_e32 v18, 0xffff0000, v79
	v_fmac_f32_e32 v22, v3, v17
	v_cvt_pk_bf16_f32 v10, v10, v11
	v_cvt_pk_bf16_f32 v11, v12, v13
	v_cvt_pk_bf16_f32 v12, v14, v15
	v_lshl_add_u64 v[14:15], v[8:9], 0, v[154:155]
	v_mul_f32_e32 v17, v22, v18
	v_cvt_pk_bf16_f32 v13, v16, v17
	global_store_dwordx4 v[14:15], v[10:13], off
	ds_read_b128 v[10:13], v233
	ds_read_b128 v[14:17], v233 offset:16
	v_lshlrev_b32_e32 v18, 16, v72
	s_waitcnt vmcnt(7) lgkmcnt(1)
	v_fma_f32 v10, v4, v10, v23
	v_mul_f32_e32 v10, v10, v18
	v_and_b32_e32 v18, 0xffff0000, v72
	v_fma_f32 v11, v5, v11, v23
	v_mul_f32_e32 v11, v11, v18
	v_lshlrev_b32_e32 v18, 16, v73
	v_fma_f32 v12, v6, v12, v23
	v_mul_f32_e32 v12, v12, v18
	v_and_b32_e32 v18, 0xffff0000, v73
	v_fma_f32 v13, v7, v13, v23
	v_mul_f32_e32 v13, v13, v18
	v_lshlrev_b32_e32 v18, 16, v74
	s_waitcnt lgkmcnt(0)
	v_fma_f32 v14, v0, v14, v23
	v_mul_f32_e32 v14, v14, v18
	v_and_b32_e32 v18, 0xffff0000, v74
	v_fma_f32 v15, v1, v15, v23
	v_mul_f32_e32 v15, v15, v18
	v_lshlrev_b32_e32 v18, 16, v75
	v_fma_f32 v16, v2, v16, v23
	v_mul_f32_e32 v16, v16, v18
	v_and_b32_e32 v18, 0xffff0000, v75
	v_fmac_f32_e32 v23, v3, v17
	v_cvt_pk_bf16_f32 v10, v10, v11
	v_cvt_pk_bf16_f32 v11, v12, v13
	v_cvt_pk_bf16_f32 v12, v14, v15
	v_lshl_add_u64 v[14:15], v[8:9], 0, v[150:151]
	v_mul_f32_e32 v17, v23, v18
	v_cvt_pk_bf16_f32 v13, v16, v17
	global_store_dwordx4 v[14:15], v[10:13], off
	ds_read_b128 v[10:13], v234
	ds_read_b128 v[14:17], v234 offset:16
	v_lshlrev_b32_e32 v18, 16, v68
	s_waitcnt vmcnt(7) lgkmcnt(1)
	v_fma_f32 v10, v4, v10, v24
	v_mul_f32_e32 v10, v10, v18
	v_and_b32_e32 v18, 0xffff0000, v68
	v_fma_f32 v11, v5, v11, v24
	v_mul_f32_e32 v11, v11, v18
	v_lshlrev_b32_e32 v18, 16, v69
	v_fma_f32 v12, v6, v12, v24
	v_mul_f32_e32 v12, v12, v18
	v_and_b32_e32 v18, 0xffff0000, v69
	v_fma_f32 v13, v7, v13, v24
	v_mul_f32_e32 v13, v13, v18
	v_lshlrev_b32_e32 v18, 16, v70
	s_waitcnt lgkmcnt(0)
	v_fma_f32 v14, v0, v14, v24
	v_mul_f32_e32 v14, v14, v18
	v_and_b32_e32 v18, 0xffff0000, v70
	v_fma_f32 v15, v1, v15, v24
	v_mul_f32_e32 v15, v15, v18
	v_lshlrev_b32_e32 v18, 16, v71
	v_fma_f32 v16, v2, v16, v24
	v_mul_f32_e32 v16, v16, v18
	v_and_b32_e32 v18, 0xffff0000, v71
	v_fmac_f32_e32 v24, v3, v17
	v_cvt_pk_bf16_f32 v10, v10, v11
	v_cvt_pk_bf16_f32 v11, v12, v13
	v_cvt_pk_bf16_f32 v12, v14, v15
	v_lshl_add_u64 v[14:15], v[8:9], 0, v[148:149]
	v_mul_f32_e32 v17, v24, v18
	v_cvt_pk_bf16_f32 v13, v16, v17
	global_store_dwordx4 v[14:15], v[10:13], off
	ds_read_b128 v[10:13], v235
	ds_read_b128 v[14:17], v235 offset:16
	v_lshlrev_b32_e32 v18, 16, v64
	s_waitcnt vmcnt(7) lgkmcnt(1)
	v_fma_f32 v4, v4, v10, v25
	v_and_b32_e32 v10, 0xffff0000, v64
	v_fma_f32 v5, v5, v11, v25
	v_mul_f32_e32 v5, v5, v10
	v_lshlrev_b32_e32 v10, 16, v65
	v_fma_f32 v6, v6, v12, v25
	v_mul_f32_e32 v6, v6, v10
	v_and_b32_e32 v10, 0xffff0000, v65
	v_fma_f32 v7, v7, v13, v25
	v_mul_f32_e32 v7, v7, v10
	v_lshlrev_b32_e32 v10, 16, v66
	s_waitcnt lgkmcnt(0)
	v_fma_f32 v0, v0, v14, v25
	v_mul_f32_e32 v10, v0, v10
	v_and_b32_e32 v0, 0xffff0000, v66
	v_fma_f32 v1, v1, v15, v25
	v_mul_f32_e32 v11, v1, v0
	v_lshlrev_b32_e32 v0, 16, v67
	v_fma_f32 v1, v2, v16, v25
	v_mul_f32_e32 v4, v4, v18
	v_mul_f32_e32 v12, v1, v0
	v_and_b32_e32 v0, 0xffff0000, v67
	v_fmac_f32_e32 v25, v3, v17
	v_mul_f32_e32 v3, v25, v0
	v_cvt_pk_bf16_f32 v0, v4, v5
	v_lshl_add_u64 v[4:5], v[8:9], 0, v[146:147]
	v_cvt_pk_bf16_f32 v1, v6, v7
	v_cvt_pk_bf16_f32 v2, v10, v11
	v_cvt_pk_bf16_f32 v3, v12, v3
	global_store_dwordx4 v[4:5], v[0:3], off
	s_barrier
	s_cbranch_scc0 .LBB0_331
.LBB0_265:
	s_ashr_i32 s72, s71, 4
	s_ashr_i32 s73, s72, 31
	s_and_b32 s97, s71, 15
	s_lshl_b64 s[72:73], s[72:73], 7
	s_lshl_b32 s76, s97, 9
	s_waitcnt lgkmcnt(0)
	v_lshl_add_u64 v[236:237], s[72:73], 0, v[96:97]
	v_lshlrev_b64 v[162:163], 13, v[236:237]
	v_lshl_add_u64 v[236:237], s[72:73], 0, v[100:101]
	v_lshlrev_b64 v[160:161], 13, v[236:237]
	v_lshl_add_u64 v[236:237], s[72:73], 0, v[102:103]
	v_lshlrev_b64 v[158:159], 13, v[236:237]
	v_lshl_add_u64 v[236:237], s[72:73], 0, v[104:105]
	v_lshlrev_b64 v[156:157], 13, v[236:237]
	v_lshl_add_u64 v[236:237], s[72:73], 0, v[106:107]
	v_lshlrev_b64 v[154:155], 13, v[236:237]
	v_lshl_add_u64 v[236:237], s[72:73], 0, v[108:109]
	v_lshlrev_b64 v[150:151], 13, v[236:237]
	v_lshl_add_u64 v[236:237], s[72:73], 0, v[110:111]
	v_lshlrev_b64 v[148:149], 13, v[236:237]
	v_lshl_add_u64 v[236:237], s[72:73], 0, v[112:113]
	v_lshlrev_b64 v[146:147], 13, v[236:237]
	v_lshl_add_u64 v[238:239], v[114:115], 0, s[76:77]
	v_lshl_add_u64 v[240:241], v[238:239], 0, v[162:163]
	global_load_dwordx4 v[0:3], v[240:241], off nt
	v_lshl_add_u64 v[236:237], s[72:73], 0, v[116:117]
	v_lshlrev_b64 v[236:237], 13, v[236:237]
	v_lshl_add_u64 v[240:241], v[238:239], 0, v[236:237]
	global_load_dwordx4 v[4:7], v[240:241], off nt
	v_lshl_add_u64 v[236:237], s[72:73], 0, v[118:119]
	v_lshlrev_b64 v[236:237], 13, v[236:237]
	v_lshl_add_u64 v[240:241], v[238:239], 0, v[236:237]
	global_load_dwordx4 v[8:11], v[240:241], off nt
	v_lshl_add_u64 v[236:237], s[72:73], 0, v[120:121]
	v_lshlrev_b64 v[236:237], 13, v[236:237]
	v_lshl_add_u64 v[240:241], v[238:239], 0, v[236:237]
	global_load_dwordx4 v[12:15], v[240:241], off nt
	v_lshl_add_u64 v[236:237], s[72:73], 0, v[122:123]
	v_lshlrev_b64 v[236:237], 13, v[236:237]
	v_lshl_add_u64 v[240:241], v[238:239], 0, v[236:237]
	global_load_dwordx4 v[16:19], v[240:241], off nt
	v_lshl_add_u64 v[236:237], s[72:73], 0, v[124:125]
	v_lshlrev_b64 v[236:237], 13, v[236:237]
	v_lshl_add_u64 v[240:241], v[238:239], 0, v[236:237]
	global_load_dwordx4 v[20:23], v[240:241], off nt
	v_lshl_add_u64 v[236:237], s[72:73], 0, v[126:127]
	v_lshlrev_b64 v[236:237], 13, v[236:237]
	v_lshl_add_u64 v[240:241], v[238:239], 0, v[236:237]
	global_load_dwordx4 v[24:27], v[240:241], off nt
	v_lshl_add_u64 v[236:237], s[72:73], 0, v[128:129]
	v_lshlrev_b64 v[236:237], 13, v[236:237]
	v_lshl_add_u64 v[240:241], v[238:239], 0, v[236:237]
	global_load_dwordx4 v[28:31], v[240:241], off nt
	s_and_saveexec_b64 s[82:83], vcc
	s_cbranch_execz .Lp2_a
	v_lshl_add_u64 v[242:243], s[72:73], 2, v[130:131]
	global_load_dword v242, v[242:243], off
; #define LAS __attribute__((address_space(3)))
; __device__ __forceinline__ unsigned pk_bf16(float lo, float hi) { return pg8::cvt_pk_bf16(lo, hi); }
; #define tid tid_of(wave)
; __device__ __forceinline__ void mix_unit(LAS unsigned char* lds, const int wid, int n, int g, const bf16_t* __restrict__ UZ, const bf16_t* __restrict__ V, const float* __restrict__ vss, ...
;     ...
;     for (int i = 0; i < 8; ++i) { const int t = (tid >> 5) + 16 * i; uu[i] = __builtin_nontemporal_load((const u32x4*)(UZ + (row0 + t) * GW + g * GDIM + cc * 8)); }
;     {
;         u32x4 vr[8];
; #pragma unroll
;         for (int i = 0; i < 8; ++i) { const int c = tid + 512 * i, s = c >> 5, cc = c & 31;
;             vr[i] = __builtin_nontemporal_load((const u32x4*)(V + (row0 + s) * GW + g * GDIM + cc * 8)); }
;         if (tid < 128) rstdL[tid] = __builtin_amdgcn_rsqf(vss[row0 + tid] * (1.0f / GW) + EPS);
; #pragma unroll
;         for (int i = 0; i < 8; ++i) { const int c = tid + 512 * i, s = c >> 5, cc = c & 31;
;             *(LAS u32x4*)(lds + 32768 + (cc >> 4) * 32768 + off_b(s, cc & 15)) = vr[i]; }
;     }
;     __syncthreads();
; #pragma unroll
;     for (int i = 0; i < 4; ++i) { const int c = tid + 512 * i, t = c >> 4, ch = c & 15, s0 = ch * 8;
;         const f32x4 w0 = *(const f32x4*)(w_s + ((size_t)g * CHUNK + t) * CHUNK + s0), w1 = *(const f32x4*)(w_s + ((size_t)g * CHUNK + t) * CHUNK + s0 + 4);
;         float wv[8] = {w0[0], w0[1], w0[2], w0[3], w1[0], w1[1], w1[2], w1[3]};
; #pragma unroll
;         for (int j = 0; j < 8; ++j) wv[j] = (s0 + j <= t) ? wv[j] * rstdL[s0 + j] : 0.f;
;         u32x4 w; w.x = pk_bf16(wv[0], wv[1]); w.y = pk_bf16(wv[2], wv[3]); w.z = pk_bf16(wv[4], wv[5]); w.w = pk_bf16(wv[6], wv[7]);
;         *(LAS u32x4*)(lds + off_b(t, ch)) = w; }
;     __syncthreads();
.Lp2_a:
	s_or_b64 exec, exec, s[82:83]
	s_lshl_b32 s82, s97, 7
	s_mov_b32 s83, 0
	v_lshl_add_u64 v[236:237], s[82:83], 0, v[134:135]
	v_lshlrev_b64 v[236:237], 9, v[236:237]
	v_lshl_add_u64 v[240:241], v[132:133], 0, v[236:237]
	global_load_dwordx4 v[32:35], v[240:241], off
	global_load_dwordx4 v[36:39], v[240:241], off offset:16
	v_lshl_add_u64 v[236:237], s[82:83], 0, v[136:137]
	v_lshlrev_b64 v[236:237], 9, v[236:237]
	v_lshl_add_u64 v[240:241], v[132:133], 0, v[236:237]
	global_load_dwordx4 v[40:43], v[240:241], off
	global_load_dwordx4 v[44:47], v[240:241], off offset:16
	v_lshl_add_u64 v[236:237], s[82:83], 0, v[138:139]
	v_lshlrev_b64 v[236:237], 9, v[236:237]
	v_lshl_add_u64 v[240:241], v[132:133], 0, v[236:237]
	global_load_dwordx4 v[48:51], v[240:241], off
	global_load_dwordx4 v[52:55], v[240:241], off offset:16
	v_lshl_add_u64 v[236:237], s[82:83], 0, v[140:141]
	v_lshlrev_b64 v[236:237], 9, v[236:237]
	v_lshl_add_u64 v[240:241], v[132:133], 0, v[236:237]
	global_load_dwordx4 v[56:59], v[240:241], off
	global_load_dwordx4 v[60:63], v[240:241], off offset:16
	v_lshl_add_u64 v[238:239], v[98:99], 0, s[76:77]
	v_lshl_add_u64 v[240:241], v[238:239], 0, v[162:163]
	global_load_dwordx4 v[92:95], v[240:241], off nt
	v_lshl_add_u64 v[240:241], v[238:239], 0, v[160:161]
	global_load_dwordx4 v[88:91], v[240:241], off nt
	v_lshl_add_u64 v[240:241], v[238:239], 0, v[158:159]
	global_load_dwordx4 v[84:87], v[240:241], off nt
	v_lshl_add_u64 v[240:241], v[238:239], 0, v[156:157]
	global_load_dwordx4 v[80:83], v[240:241], off nt
	v_lshl_add_u64 v[240:241], v[238:239], 0, v[154:155]
	global_load_dwordx4 v[76:79], v[240:241], off nt
	v_lshl_add_u64 v[240:241], v[238:239], 0, v[150:151]
	global_load_dwordx4 v[72:75], v[240:241], off nt
	v_lshl_add_u64 v[240:241], v[238:239], 0, v[148:149]
	global_load_dwordx4 v[68:71], v[240:241], off nt
	v_lshl_add_u64 v[240:241], v[238:239], 0, v[146:147]
	global_load_dwordx4 v[64:67], v[240:241], off nt
	s_and_saveexec_b64 s[82:83], vcc
	s_cbranch_execz .Lp2_b
	s_waitcnt vmcnt(16)
	v_fmamk_f32 v242, v242, 0x39800000, v205
	v_rsq_f32_e32 v242, v242
	s_nop 0
	ds_write_b32 v153, v242
.Lp2_b:
	s_or_b64 exec, exec, s[82:83]
	s_lshl_b32 s76, s97, 7
	s_waitcnt vmcnt(16)
	ds_write_b128 v206, v[0:3] offset:32768
	ds_write_b128 v207, v[4:7] offset:32768
	ds_write_b128 v208, v[8:11] offset:32768
	ds_write_b128 v209, v[12:15] offset:32768
	ds_write_b128 v210, v[16:19] offset:32768
	ds_write_b128 v211, v[20:23] offset:32768
	ds_write_b128 v212, v[24:27] offset:32768
	ds_write_b128 v213, v[28:31] offset:32768
	s_waitcnt lgkmcnt(0)
	s_barrier
	ds_read_b128 v[0:3], v164
	ds_read_b128 v[4:7], v164 offset:16
	s_waitcnt vmcnt(8) lgkmcnt(0)
	v_mul_f32_e32 v8, v32, v0
	v_mul_f32_e32 v9, v33, v1
	v_mul_f32_e32 v10, v34, v2
	v_mul_f32_e32 v11, v35, v3
	v_mul_f32_e32 v12, v36, v4
	v_mul_f32_e32 v13, v37, v5
	v_mul_f32_e32 v14, v38, v6
	v_mul_f32_e32 v15, v39, v7
	v_cndmask_b32_e64 v8, 0, v8, s[0:1]
	v_cndmask_b32_e64 v9, 0, v9, s[4:5]
	v_cndmask_b32_e64 v10, 0, v10, s[6:7]
	v_cndmask_b32_e64 v11, 0, v11, s[8:9]
	v_cndmask_b32_e64 v12, 0, v12, s[10:11]
	v_cndmask_b32_e64 v13, 0, v13, s[12:13]
	v_cndmask_b32_e64 v14, 0, v14, s[14:15]
	v_cndmask_b32_e64 v15, 0, v15, s[16:17]
	v_cvt_pk_bf16_f32 v16, v8, v9
	v_cvt_pk_bf16_f32 v17, v10, v11
	v_cvt_pk_bf16_f32 v18, v12, v13
	v_cvt_pk_bf16_f32 v19, v14, v15
	ds_write_b128 v214, v[16:19]
	v_mul_f32_e32 v8, v40, v0
	v_mul_f32_e32 v9, v41, v1
	v_mul_f32_e32 v10, v42, v2
	v_mul_f32_e32 v11, v43, v3
	v_mul_f32_e32 v12, v44, v4
	v_mul_f32_e32 v13, v45, v5
	v_mul_f32_e32 v14, v46, v6
	v_mul_f32_e32 v15, v47, v7
	v_cndmask_b32_e64 v8, 0, v8, s[18:19]
	v_cndmask_b32_e64 v9, 0, v9, s[20:21]
	v_cndmask_b32_e64 v10, 0, v10, s[22:23]
	v_cndmask_b32_e64 v11, 0, v11, s[24:25]
	v_cndmask_b32_e64 v12, 0, v12, s[26:27]
	v_cndmask_b32_e64 v13, 0, v13, s[28:29]
	v_cndmask_b32_e64 v14, 0, v14, s[30:31]
	v_cndmask_b32_e64 v15, 0, v15, s[34:35]
	v_cvt_pk_bf16_f32 v20, v8, v9
	v_cvt_pk_bf16_f32 v21, v10, v11
	v_cvt_pk_bf16_f32 v22, v12, v13
	v_cvt_pk_bf16_f32 v23, v14, v15
	ds_write_b128 v215, v[20:23]
	v_mul_f32_e32 v8, v48, v0
	v_mul_f32_e32 v9, v49, v1
	v_mul_f32_e32 v10, v50, v2
	v_mul_f32_e32 v11, v51, v3
	v_mul_f32_e32 v12, v52, v4
	v_mul_f32_e32 v13, v53, v5
	v_mul_f32_e32 v14, v54, v6
	v_mul_f32_e32 v15, v55, v7
	v_cndmask_b32_e64 v8, 0, v8, s[36:37]
	v_cndmask_b32_e64 v9, 0, v9, s[38:39]
	v_cndmask_b32_e64 v10, 0, v10, s[40:41]
	v_cndmask_b32_e64 v11, 0, v11, s[42:43]
	v_cndmask_b32_e64 v12, 0, v12, s[44:45]
	v_cndmask_b32_e64 v13, 0, v13, s[46:47]
	v_cndmask_b32_e64 v14, 0, v14, s[48:49]
	v_cndmask_b32_e64 v15, 0, v15, s[50:51]
	v_cvt_pk_bf16_f32 v16, v8, v9
	v_cvt_pk_bf16_f32 v17, v10, v11
	v_cvt_pk_bf16_f32 v18, v12, v13
	v_cvt_pk_bf16_f32 v19, v14, v15
	ds_write_b128 v216, v[16:19]
	v_mul_f32_e32 v8, v56, v0
	v_mul_f32_e32 v9, v57, v1
	v_mul_f32_e32 v10, v58, v2
	v_mul_f32_e32 v11, v59, v3
	v_mul_f32_e32 v12, v60, v4
	v_mul_f32_e32 v13, v61, v5
	v_mul_f32_e32 v14, v62, v6
	v_mul_f32_e32 v15, v63, v7
	v_cndmask_b32_e64 v8, 0, v8, s[52:53]
	v_cndmask_b32_e64 v9, 0, v9, s[54:55]
	v_cndmask_b32_e64 v10, 0, v10, s[56:57]
	v_cndmask_b32_e64 v11, 0, v11, s[58:59]
	v_cndmask_b32_e64 v12, 0, v12, s[60:61]
	v_cndmask_b32_e64 v13, 0, v13, s[62:63]
	v_cndmask_b32_e64 v14, 0, v14, s[64:65]
	v_cndmask_b32_e64 v15, 0, v15, s[66:67]
	v_cvt_pk_bf16_f32 v20, v8, v9
	v_cvt_pk_bf16_f32 v21, v10, v11
	v_cvt_pk_bf16_f32 v22, v12, v13
	v_cvt_pk_bf16_f32 v23, v14, v15
	ds_write_b128 v217, v[20:23]
	s_waitcnt lgkmcnt(0)
	s_barrier
	s_branch .Lp2_mfma
